# attention key-tile loop: lane-exchange index registers hoisted out of the loop; score negation via v_pk_mul_f32 pairs (fewer VALU per tile)
# speedup vs baseline: 1.0020x; 1.0020x over previous
; __device__ __forceinline__ void item_attn(const Params& p, int l, int aidx) {
;     ...
;   bf16x8 qf[2][2];
;   bool rowv[2];
; #pragma unroll
;   for (int n = 0; n < 2; ++n) {
;     int row = 32 * wid + 16 * n + fr;
;     rowv[n] = row < nq;
; #pragma unroll
;     for (int ks = 0; ks < 2; ++ks) {
;       bf16x8 z = {0, 0, 0, 0, 0, 0, 0, 0};
;       if (rowv[n]) z = *reinterpret_cast<const bf16x8*>(p.sq + (tokq0 + row) * 512 + hd * 64 + ks * 32 + fq * 8);
;       qf[n][ks] = z;
;     }
;   }
;     ...
;             const float g1 = __shfl_xor(G, 16), g2 = __shfl_xor(G, 32), g3 = __shfl_xor(G, 48);
.LBB0_509:
	v_xor_b32_e32 v241, 16, v215
	v_xor_b32_e32 v242, 32, v215
	v_xor_b32_e32 v243, 48, v215
	v_lshlrev_b32_e32 v241, 2, v241
	v_lshlrev_b32_e32 v242, 2, v242
	v_lshlrev_b32_e32 v243, 2, v243
	s_ashr_i32 s2, s2, 6
	v_and_b32_e32 v33, 15, v32
	s_lshl_b32 s21, s2, 5
	v_readlane_b32 s48, v247, 7
	v_or_b32_e32 v84, s21, v33
	s_lshl_b64 s[44:45], s[28:29], 1
	v_readlane_b32 s52, v247, 11
	v_readlane_b32 s53, v247, 12
	s_add_u32 s0, s52, s44
	v_ashrrev_i32_e32 v85, 31, v84
	s_addc_u32 s1, s53, s45
	v_and_b32_e32 v190, 48, v32
	v_lshl_add_u64 v[0:1], s[34:35], 0, v[84:85]
	v_lshl_add_u64 v[8:9], s[0:1], 0, v[190:191]
	v_lshlrev_b64 v[82:83], 10, v[0:1]
	v_cmp_gt_i32_e64 s[8:9], s47, v84
	v_lshl_add_u64 v[10:11], v[8:9], 0, v[82:83]
	v_mov_b32_e32 v0, 0
	v_mov_b32_e32 v4, 0
	v_mov_b32_e32 v5, 0
	v_mov_b32_e32 v6, 0
	v_mov_b32_e32 v7, 0
	v_readlane_b32 s49, v247, 8
	v_readlane_b32 s50, v247, 9
	v_readlane_b32 s51, v247, 10
	v_readlane_b32 s54, v247, 13
	v_readlane_b32 s55, v247, 14
	v_readlane_b32 s56, v247, 15
	v_readlane_b32 s57, v247, 16
	v_readlane_b32 s58, v247, 17
	v_readlane_b32 s59, v247, 18
	v_readlane_b32 s60, v247, 19
	v_readlane_b32 s61, v247, 20
	v_readlane_b32 s62, v247, 21
	v_readlane_b32 s63, v247, 22
	s_and_saveexec_b64 s[0:1], s[8:9]
	s_cbranch_execz .LBB0_511
	global_load_dwordx4 v[4:7], v[10:11], off

; __device__ __forceinline__ float fexp(float x) { return __builtin_amdgcn_exp2f(x * 1.44269504f); }
; __device__ __forceinline__ void item_attn(const Params& p, int l, int aidx) {
;     ...
;       for (int m = 0; m < 4; ++m) {
;         bf16x8 a0 = *reinterpret_cast<const bf16x8*>(Ks + (m * 16 + fr) * 72 + fq * 8);
;         bf16x8 a1 = *reinterpret_cast<const bf16x8*>(Ks + (m * 16 + fr) * 72 + 32 + fq * 8);
; #pragma unroll
;         for (int n = 0; n < 2; ++n) {
;           f32x4 zz = f32x4{0.f, 0.f, 0.f, 0.f};
;           zz = __builtin_amdgcn_mfma_f32_16x16x32_bf16(a0, qf[n][0], zz, 0, 0, 0);
;           zz = __builtin_amdgcn_mfma_f32_16x16x32_bf16(a1, qf[n][1], zz, 0, 0, 0);
;           z[m][n] = zz;
;         }
;       }
;       unsigned pk[4][2][2];
;       auto sb_weights = [&](auto MASKED) {
; #pragma unroll
;         for (int n = 0; n < 2; ++n) {
;           const int qpos = qpos0 + 32 * wid + 16 * n + fr;
;           float wgt[4][4], excl[4][4], later[4], TT[4];
; #pragma unroll
;           for (int m = 0; m < 4; ++m) {
;             float f[4];
; #pragma unroll
;             for (int j = 0; j < 4; ++j) {
;               const float e = fexp(fminf(-z[m][n][j], 80.f));
;               const float sg = __builtin_amdgcn_rcpf(1.f + e);
;               if (decltype(MASKED)::value) {
;                 const bool ok = (kt * 64 + m * 16 + fq * 4 + j) < qpos;
;                 wgt[m][j] = ok ? sg : 0.f;
;                 f[j] = ok ? e * sg : 1.f;
;               } else { wgt[m][j] = sg; f[j] = e * sg; }
;             }
;             excl[m][3] = 1.f; excl[m][2] = f[3]; excl[m][1] = f[3] * f[2]; excl[m][0] = excl[m][1] * f[1];
;             const float G = excl[m][0] * f[0];
;             const float g1 = __shfl_xor(G, 16), g2 = __shfl_xor(G, 32), g3 = __shfl_xor(G, 48);
;             later[m] = ((fq ^ 1) > fq ? g1 : 1.f) * ((fq ^ 2) > fq ? g2 : 1.f) * ((fq ^ 3) > fq ? g3 : 1.f);
;             TT[m] = (G * g1) * (g2 * g3);
;           }
.LBB0_687:
	s_xor_b64 s[0:1], s[0:1], -1
	s_andn2_b64 vcc, exec, s[0:1]
	s_mov_b64 s[0:1], -1
	s_cbranch_vccnz .LBB0_694
	s_cmp_ge_i32 s24, s51
	s_mov_b64 s[0:1], 0
	s_cbranch_scc1 .LBB0_694
	ds_read_b128 v[64:67], v118
	ds_read_b128 v[68:71], v118 offset:64
	s_nop 0
	s_nop 0
	s_nop 0
	s_waitcnt lgkmcnt(1)
	v_mfma_f32_16x16x32_bf16 v[72:75], v[64:67], v[4:7], 0
	s_nop 0
	s_add_i32 s0, s49, 0x7f
	s_cmp_ge_i32 s0, s50
	v_mfma_f32_16x16x32_bf16 v[64:67], v[64:67], v[12:15], 0
	s_nop 0
	s_nop 0
	s_nop 0
	s_waitcnt lgkmcnt(0)
	v_mfma_f32_16x16x32_bf16 v[72:75], v[68:71], v[0:3], v[72:75]
	s_nop 0
	s_mov_b64 s[0:1], -1
	v_mfma_f32_16x16x32_bf16 v[64:67], v[68:71], v[8:11], v[64:67]
	ds_read_b128 v[68:71], v118 offset:2304
	ds_read_b128 v[76:79], v118 offset:2368
	s_nop 0
	s_nop 1
	s_nop 0
	s_waitcnt lgkmcnt(1)
	v_mfma_f32_16x16x32_bf16 v[92:95], v[68:71], v[4:7], 0
	v_pk_mul_f32 v[160:161], v[72:73], 1.0 op_sel_hi:[1,0] neg_lo:[1,0] neg_hi:[1,0]
	s_nop 0
	v_pk_mul_f32 v[158:159], v[74:75], 1.0 op_sel:[1,0] op_sel_hi:[0,0] neg_lo:[1,0] neg_hi:[1,0]
	v_mfma_f32_16x16x32_bf16 v[68:71], v[68:71], v[12:15], 0
	s_nop 0
	v_pk_mul_f32 v[144:145], v[64:65], 1.0 op_sel:[1,0] op_sel_hi:[0,0] neg_lo:[1,0] neg_hi:[1,0]
	s_nop 0
	s_waitcnt lgkmcnt(0)
	v_mfma_f32_16x16x32_bf16 v[92:95], v[76:79], v[0:3], v[92:95]
	v_pk_mul_f32 v[142:143], v[66:67], 1.0 op_sel_hi:[1,0] neg_lo:[1,0] neg_hi:[1,0]
	v_mfma_f32_16x16x32_bf16 v[68:71], v[76:79], v[8:11], v[68:71]
	ds_read_b128 v[76:79], v118 offset:4608
	ds_read_b128 v[96:99], v118 offset:4672
	s_nop 3
	s_nop 0
	v_pk_mul_f32 v[156:157], v[92:93], 1.0 op_sel:[1,0] op_sel_hi:[0,0] neg_lo:[1,0] neg_hi:[1,0]
	s_waitcnt lgkmcnt(1)
	v_mfma_f32_16x16x32_bf16 v[128:131], v[76:79], v[4:7], 0
	s_nop 0
	v_pk_mul_f32 v[154:155], v[94:95], 1.0 op_sel_hi:[1,0] neg_lo:[1,0] neg_hi:[1,0]
	v_mfma_f32_16x16x32_bf16 v[76:79], v[76:79], v[12:15], 0
	s_waitcnt lgkmcnt(0)
	v_mfma_f32_16x16x32_bf16 v[130:133], v[96:99], v[0:3], v[128:131]
	v_mfma_f32_16x16x32_bf16 v[76:79], v[96:99], v[8:11], v[76:79]
	ds_read_b128 v[96:99], v118 offset:6912
	ds_read_b128 v[134:137], v118 offset:6976
	s_nop 0
	s_nop 0
	s_waitcnt lgkmcnt(1)
	v_mfma_f32_16x16x32_bf16 v[138:141], v[96:99], v[4:7], 0
	s_nop 0
	v_max_f32_e64 v151, -v130, -v130
	v_max_f32_e64 v153, -v131, -v131
	v_mfma_f32_16x16x32_bf16 v[96:99], v[96:99], v[12:15], 0
	s_nop 0
	s_nop 0
	v_max_f32_e64 v152, -v132, -v132
	s_waitcnt lgkmcnt(0)
	v_mfma_f32_16x16x32_bf16 v[138:141], v[134:137], v[0:3], v[138:141]
	v_max_f32_e64 v150, -v133, -v133
	v_mfma_f32_16x16x32_bf16 v[96:99], v[134:137], v[8:11], v[96:99]
	s_nop 0
	s_nop 4
	v_max_f32_e64 v147, -v138, -v138
	v_max_f32_e64 v149, -v139, -v139
	v_max_f32_e64 v148, -v140, -v140
	v_max_f32_e64 v146, -v141, -v141
	s_nop 0
	v_pk_mul_f32 v[140:141], v[68:69], 1.0 op_sel:[1,0] op_sel_hi:[0,0] neg_lo:[1,0] neg_hi:[1,0]
	s_nop 0
	v_pk_mul_f32 v[138:139], v[70:71], 1.0 op_sel:[1,0] op_sel_hi:[0,0] neg_lo:[1,0] neg_hi:[1,0]
	v_pk_mul_f32 v[136:137], v[76:77], 1.0 op_sel:[1,0] op_sel_hi:[0,0] neg_lo:[1,0] neg_hi:[1,0]
	s_nop 0
	v_pk_mul_f32 v[134:135], v[78:79], 1.0 op_sel:[1,0] op_sel_hi:[0,0] neg_lo:[1,0] neg_hi:[1,0]
	s_nop 0
	v_pk_mul_f32 v[132:133], v[96:97], 1.0 op_sel_hi:[1,0] neg_lo:[1,0] neg_hi:[1,0]
	s_nop 0
	v_pk_mul_f32 v[130:131], v[98:99], 1.0 op_sel:[1,0] op_sel_hi:[0,0] neg_lo:[1,0] neg_hi:[1,0]
	s_cbranch_scc0 .LBB0_691
	v_min_f32_e32 v64, 0x42a00000, v160
	v_min_f32_e32 v65, 0x42a00000, v161
	v_mul_f32_e32 v64, 0x3fb8aa3b, v64
	v_mul_f32_e32 v65, 0x3fb8aa3b, v65
	v_exp_f32_e32 v67, v64
	v_exp_f32_e32 v69, v65
	v_min_f32_e32 v65, 0x42a00000, v159
	v_mul_f32_e32 v65, 0x3fb8aa3b, v65
	v_exp_f32_e32 v65, v65
	v_min_f32_e32 v68, 0x42a00000, v157
	v_add_f32_e32 v66, 1.0, v67
	v_mul_f32_e32 v68, 0x3fb8aa3b, v68
	v_rcp_f32_e32 v73, v66
	v_add_f32_e32 v66, 1.0, v69
	v_exp_f32_e32 v68, v68
	v_rcp_f32_e32 v75, v66
	v_add_f32_e32 v66, 1.0, v65
	v_rcp_f32_e32 v77, v66
	v_min_f32_e32 v66, 0x42a00000, v158
	v_mul_f32_e32 v66, 0x3fb8aa3b, v66
	v_min_f32_e32 v70, 0x42a00000, v156
	v_exp_f32_e32 v71, v66
	v_add_f32_e32 v66, 1.0, v68
	v_mul_f32_e32 v70, 0x3fb8aa3b, v70
	v_rcp_f32_e32 v66, v66
	v_exp_f32_e32 v70, v70
	v_add_u32_e32 v64, s49, v114
	v_add_u32_e32 v180, 0x50, v64
	v_cmp_lt_i32_e32 vcc, v180, v85
	v_min_f32_e32 v74, 0x42a00000, v154
	v_mul_f32_e32 v74, 0x3fb8aa3b, v74
	v_cndmask_b32_e32 v72, 0, v66, vcc
	v_mul_f32_e32 v66, v68, v66
	v_add_f32_e32 v68, 1.0, v70
	v_rcp_f32_e32 v68, v68
	v_exp_f32_e32 v74, v74
	v_add_u32_e32 v181, 0x51, v64
	v_cndmask_b32_e32 v66, 1.0, v66, vcc
	v_cmp_lt_i32_e32 vcc, v181, v85
	v_min_f32_e32 v78, 0x42a00000, v155
	v_mul_f32_e32 v78, 0x3fb8aa3b, v78
	v_cndmask_b32_e32 v76, 0, v68, vcc
	v_mul_f32_e32 v68, v70, v68
	v_add_f32_e32 v70, 1.0, v74
	v_rcp_f32_e32 v70, v70
	v_exp_f32_e32 v78, v78
	v_add_u32_e32 v182, 0x52, v64
	v_cndmask_b32_e32 v68, 1.0, v68, vcc
	v_cmp_lt_i32_e32 vcc, v182, v85
	v_add_u32_e32 v183, 0x53, v64
	v_min_f32_e32 v98, 0x42a00000, v153
	v_cndmask_b32_e32 v92, 0, v70, vcc
	v_mul_f32_e32 v70, v74, v70
	v_add_f32_e32 v74, 1.0, v78
	v_rcp_f32_e32 v74, v74
	v_cndmask_b32_e32 v70, 1.0, v70, vcc
	v_cmp_lt_i32_e32 vcc, v183, v85
	v_mul_f32_e32 v98, 0x3fb8aa3b, v98
	v_exp_f32_e32 v98, v98
	v_cndmask_b32_e32 v101, 0, v74, vcc
	v_mul_f32_e32 v74, v78, v74
	v_cndmask_b32_e32 v94, 1.0, v74, vcc
	v_mul_f32_e32 v70, v94, v70
	v_mul_f32_e32 v68, v68, v70
	v_mul_f32_e32 v66, v66, v68
	ds_bpermute_b32 v74, v241, v66
	ds_bpermute_b32 v78, v242, v66
	ds_bpermute_b32 v95, v243, v66
	v_add_u32_e32 v184, 0x60, v64
	v_cmp_lt_i32_e32 vcc, v184, v85
	s_waitcnt lgkmcnt(2)
	v_cndmask_b32_e64 v93, 1.0, v74, s[14:15]
	s_waitcnt lgkmcnt(1)
; __device__ __forceinline__ float fexp(float x) { return __builtin_amdgcn_exp2f(x * 1.44269504f); }
; __device__ __forceinline__ unsigned pack2(float a, float b) { unsigned r; asm volatile("v_cvt_pk_bf16_f32 %0, %1, %2" : "=v"(r) : "v"(a), "v"(b)); return r; }
; __device__ __forceinline__ void item_attn(const Params& p, int l, int aidx) {
;     ...
;             float f[4];
; #pragma unroll
;             for (int j = 0; j < 4; ++j) {
;               const float e = fexp(fminf(-z[m][n][j], 80.f));
;               const float sg = __builtin_amdgcn_rcpf(1.f + e);
;               if (decltype(MASKED)::value) {
;                 const bool ok = (kt * 64 + m * 16 + fq * 4 + j) < qpos;
;                 wgt[m][j] = ok ? sg : 0.f;
;                 f[j] = ok ? e * sg : 1.f;
;               } else { wgt[m][j] = sg; f[j] = e * sg; }
;             }
;             excl[m][3] = 1.f; excl[m][2] = f[3]; excl[m][1] = f[3] * f[2]; excl[m][0] = excl[m][1] * f[1];
;             const float G = excl[m][0] * f[0];
;             const float g1 = __shfl_xor(G, 16), g2 = __shfl_xor(G, 32), g3 = __shfl_xor(G, 48);
;             later[m] = ((fq ^ 1) > fq ? g1 : 1.f) * ((fq ^ 2) > fq ? g2 : 1.f) * ((fq ^ 3) > fq ? g3 : 1.f);
;             TT[m] = (G * g1) * (g2 * g3);
;           }
;           float lm[4]; lm[3] = carry[n]; lm[2] = lm[3] * TT[3]; lm[1] = lm[2] * TT[2]; lm[0] = lm[1] * TT[1];
; #pragma unroll
;           for (int m = 0; m < 4; ++m) {
;             const float base = later[m] * lm[m];
;             float pv[4];
; #pragma unroll
;             for (int j = 0; j < 4; ++j) pv[j] = wgt[m][j] * excl[m][j] * base;
;             pk[m][n][0] = pack2(pv[0], pv[1]); pk[m][n][1] = pack2(pv[2], pv[3]);
;           }
;           carry[n] = lm[0] * TT[0];
	v_cndmask_b32_e64 v96, 1.0, v78, s[16:17]
	v_mul_f32_e32 v93, v93, v96
	v_min_f32_e32 v96, 0x42a00000, v151
	v_mul_f32_e32 v96, 0x3fb8aa3b, v96
	v_exp_f32_e32 v96, v96
	s_waitcnt lgkmcnt(0)
	v_cndmask_b32_e64 v97, 1.0, v95, s[18:19]
	v_mul_f32_e32 v93, v97, v93
	v_min_f32_e32 v99, 0x42a00000, v152
	v_add_f32_e32 v97, 1.0, v96
	v_rcp_f32_e32 v97, v97
	v_mul_f32_e32 v99, 0x3fb8aa3b, v99
	v_exp_f32_e32 v99, v99
	v_add_u32_e32 v185, 0x61, v64
	v_cndmask_b32_e32 v169, 0, v97, vcc
	v_mul_f32_e32 v96, v96, v97
	v_add_f32_e32 v97, 1.0, v98
	v_rcp_f32_e32 v97, v97
	v_cndmask_b32_e32 v96, 1.0, v96, vcc
	v_cmp_lt_i32_e32 vcc, v185, v85
	v_add_u32_e32 v187, 0x62, v64
	v_mul_f32_e32 v164, v78, v95
	v_cndmask_b32_e32 v186, 0, v97, vcc
	v_mul_f32_e32 v97, v98, v97
	v_add_f32_e32 v98, 1.0, v99
	v_rcp_f32_e32 v100, v98
	v_min_f32_e32 v98, 0x42a00000, v150
	v_mul_f32_e32 v98, 0x3fb8aa3b, v98
	v_exp_f32_e32 v162, v98
	v_cndmask_b32_e32 v97, 1.0, v97, vcc
	v_cmp_lt_i32_e32 vcc, v187, v85
	v_mul_f32_e32 v99, v99, v100
	v_min_f32_e32 v78, 0x42a00000, v147
	v_cndmask_b32_e32 v98, 0, v100, vcc
	v_add_f32_e32 v100, 1.0, v162
	v_rcp_f32_e32 v100, v100
	v_add_u32_e32 v199, 0x63, v64
	v_mul_f32_e32 v78, 0x3fb8aa3b, v78
	v_cndmask_b32_e32 v99, 1.0, v99, vcc
	v_cmp_lt_i32_e32 vcc, v199, v85
	v_exp_f32_e32 v78, v78
	v_add_u32_e32 v203, 0x70, v64
	v_cndmask_b32_e32 v200, 0, v100, vcc
	v_mul_f32_e32 v100, v162, v100
	v_cndmask_b32_e32 v100, 1.0, v100, vcc
	v_mul_f32_e32 v201, v100, v99
	v_min_f32_e32 v99, 0x42a00000, v149
	v_add_f32_e32 v95, 1.0, v78
	v_mul_f32_e32 v99, 0x3fb8aa3b, v99
	v_rcp_f32_e32 v95, v95
	v_exp_f32_e32 v99, v99
	v_cmp_lt_i32_e32 vcc, v203, v85
	v_min_f32_e32 v165, 0x42a00000, v148
	v_mul_f32_e32 v78, v78, v95
	v_cndmask_b32_e32 v204, 0, v95, vcc
	v_add_f32_e32 v95, 1.0, v99
	v_mul_f32_e32 v165, 0x3fb8aa3b, v165
	v_rcp_f32_e32 v95, v95
	v_exp_f32_e32 v165, v165
	v_add_u32_e32 v205, 0x71, v64
	v_cndmask_b32_e32 v78, 1.0, v78, vcc
	v_cmp_lt_i32_e32 vcc, v205, v85
	v_min_f32_e32 v167, 0x42a00000, v146
	v_mul_f32_e32 v167, 0x3fb8aa3b, v167
	v_cndmask_b32_e32 v206, 0, v95, vcc
	v_mul_f32_e32 v95, v99, v95
	v_add_f32_e32 v99, 1.0, v165
	v_rcp_f32_e32 v99, v99
	v_exp_f32_e32 v167, v167
	v_add_u32_e32 v207, 0x72, v64
	v_cndmask_b32_e32 v95, 1.0, v95, vcc
	v_cmp_lt_i32_e32 vcc, v207, v85
	v_add_u32_e32 v218, 0x73, v64
	v_add_u32_e32 v178, 64, v64
	v_cndmask_b32_e32 v168, 0, v99, vcc
	v_mul_f32_e32 v99, v165, v99
	v_add_f32_e32 v165, 1.0, v167
	v_rcp_f32_e32 v165, v165
	v_cndmask_b32_e32 v99, 1.0, v99, vcc
	v_cmp_lt_i32_e32 vcc, v218, v85
	v_add_u32_e32 v179, 0x41, v64
	v_mul_f32_e32 v202, v97, v201
	v_cndmask_b32_e32 v64, 0, v165, vcc
	v_mul_f32_e32 v165, v167, v165
	v_cndmask_b32_e32 v170, 1.0, v165, vcc
	v_mul_f32_e32 v97, v96, v202
	v_mul_f32_e32 v219, v170, v99
	ds_bpermute_b32 v163, v241, v97
	ds_bpermute_b32 v96, v242, v97
	v_mul_f32_e32 v220, v95, v219
	ds_bpermute_b32 v166, v243, v97
	v_mul_f32_e32 v172, v78, v220
	ds_bpermute_b32 v173, v242, v172
	ds_bpermute_b32 v174, v241, v172
	ds_bpermute_b32 v175, v243, v172
	v_mul_f32_e32 v162, v66, v74
	s_waitcnt lgkmcnt(5)
	v_cndmask_b32_e64 v66, 1.0, v163, s[14:15]
	s_waitcnt lgkmcnt(4)
	v_cndmask_b32_e64 v74, 1.0, v96, s[16:17]
	v_mul_f32_e32 v66, v66, v74
	s_waitcnt lgkmcnt(3)
	v_cndmask_b32_e64 v74, 1.0, v166, s[18:19]
	v_mul_f32_e32 v99, v74, v66
	s_waitcnt lgkmcnt(2)
	v_cndmask_b32_e64 v66, 1.0, v173, s[16:17]
	s_waitcnt lgkmcnt(0)
	v_pk_mul_f32 v[172:173], v[172:173], v[174:175]
	v_mul_f32_e32 v176, v97, v163
	v_mov_b32_e32 v97, v172
	v_mov_b32_e32 v167, v173
	v_pk_mul_f32 v[96:97], v[96:97], v[166:167]
	v_mov_b32_e32 v177, v91
	v_pk_mul_f32 v[166:167], v[176:177], v[96:97]
	v_cndmask_b32_e64 v74, 1.0, v174, s[14:15]
	v_mov_b32_e32 v163, v166
	v_mov_b32_e32 v165, v167
	v_pk_mul_f32 v[96:97], v[162:163], v[164:165]
	v_mul_f32_e32 v66, v74, v66
	v_mov_b32_e32 v95, v97
	v_cndmask_b32_e64 v74, 1.0, v175, s[18:19]
	v_pk_mul_f32 v[92:93], v[92:93], v[94:95]
	v_mul_f32_e32 v171, v74, v66
	v_mul_f32_e32 v66, v72, v68
	v_mul_f32_e32 v68, v76, v70
	v_mul_f32_e32 v176, v101, v93
	v_mov_b32_e32 v101, v167
	v_mul_f32_e32 v95, v66, v93
	v_mul_f32_e32 v163, v68, v93
	v_mul_f32_e32 v165, v92, v93
	v_mul_f32_e32 v66, v169, v202
	v_mul_f32_e32 v68, v186, v201
	v_pk_mul_f32 v[92:93], v[98:99], v[100:101]
	v_mov_b32_e32 v169, v91
	v_min_f32_e32 v78, 0x42a00000, v141
	v_mul_f32_e32 v99, v66, v93
	v_mul_f32_e32 v101, v68, v93
	v_mul_f32_e32 v186, v92, v93
	v_mul_f32_e32 v200, v200, v93
	v_pk_mul_f32 v[92:93], v[168:169], v[170:171]
	v_mul_f32_e32 v78, 0x3fb8aa3b, v78
	v_mul_f32_e32 v66, v204, v220
	v_mul_f32_e32 v204, v92, v93
	v_exp_f32_e32 v92, v78
	v_min_f32_e32 v98, 0x42a00000, v140
	v_mul_f32_e32 v98, 0x3fb8aa3b, v98
	v_exp_f32_e32 v98, v98
	v_add_f32_e32 v94, 1.0, v92
	v_rcp_f32_e32 v94, v94
	v_cmp_lt_i32_e32 vcc, v180, v88
	v_mul_f32_e32 v68, v206, v219
	v_min_f32_e32 v162, 0x42a00000, v138
	v_cndmask_b32_e32 v206, 0, v94, vcc
	v_mul_f32_e32 v92, v92, v94
	v_min_f32_e32 v94, 0x42a00000, v139
	v_cndmask_b32_e32 v100, 1.0, v92, vcc
	v_add_f32_e32 v92, 1.0, v98
	v_mul_f32_e32 v94, 0x3fb8aa3b, v94
	v_rcp_f32_e32 v92, v92
	v_exp_f32_e32 v94, v94
	v_mul_f32_e32 v162, 0x3fb8aa3b, v162
	v_exp_f32_e32 v162, v162
	v_cmp_lt_i32_e32 vcc, v181, v88
	v_mul_f32_e32 v201, v66, v93
	v_min_f32_e32 v66, 0x42a00000, v145
	v_cndmask_b32_e32 v219, 0, v92, vcc
	v_mul_f32_e32 v92, v98, v92
	v_add_f32_e32 v98, 1.0, v94
	v_rcp_f32_e32 v98, v98
	v_add_f32_e32 v166, 1.0, v162
	v_rcp_f32_e32 v166, v166
	v_cndmask_b32_e32 v164, 1.0, v92, vcc
	v_cmp_lt_i32_e32 vcc, v182, v88
	v_mul_f32_e32 v94, v94, v98
	v_mul_f32_e32 v66, 0x3fb8aa3b, v66
; __device__ __forceinline__ float fexp(float x) { return __builtin_amdgcn_exp2f(x * 1.44269504f); }
; __device__ __forceinline__ unsigned pack2(float a, float b) { unsigned r; asm volatile("v_cvt_pk_bf16_f32 %0, %1, %2" : "=v"(r) : "v"(a), "v"(b)); return r; }
; __device__ __forceinline__ void item_attn(const Params& p, int l, int aidx) {
;     ...
;             float f[4];
; #pragma unroll
;             for (int j = 0; j < 4; ++j) {
;               const float e = fexp(fminf(-z[m][n][j], 80.f));
;               const float sg = __builtin_amdgcn_rcpf(1.f + e);
;               if (decltype(MASKED)::value) {
;                 const bool ok = (kt * 64 + m * 16 + fq * 4 + j) < qpos;
;                 wgt[m][j] = ok ? sg : 0.f;
;                 f[j] = ok ? e * sg : 1.f;
;               } else { wgt[m][j] = sg; f[j] = e * sg; }
;             }
;             excl[m][3] = 1.f; excl[m][2] = f[3]; excl[m][1] = f[3] * f[2]; excl[m][0] = excl[m][1] * f[1];
;             const float G = excl[m][0] * f[0];
;             const float g1 = __shfl_xor(G, 16), g2 = __shfl_xor(G, 32), g3 = __shfl_xor(G, 48);
;             later[m] = ((fq ^ 1) > fq ? g1 : 1.f) * ((fq ^ 2) > fq ? g2 : 1.f) * ((fq ^ 3) > fq ? g3 : 1.f);
;             TT[m] = (G * g1) * (g2 * g3);
;           }
;           float lm[4]; lm[3] = carry[n]; lm[2] = lm[3] * TT[3]; lm[1] = lm[2] * TT[2]; lm[0] = lm[1] * TT[1];
; #pragma unroll
;           for (int m = 0; m < 4; ++m) {
;             const float base = later[m] * lm[m];
;             float pv[4];
; #pragma unroll
;             for (int j = 0; j < 4; ++j) pv[j] = wgt[m][j] * excl[m][j] * base;
;             pk[m][n][0] = pack2(pv[0], pv[1]); pk[m][n][1] = pack2(pv[2], pv[3]);
;           }
;           carry[n] = lm[0] * TT[0];
	v_cndmask_b32_e32 v92, 0, v98, vcc
	v_cndmask_b32_e32 v98, 1.0, v94, vcc
	v_mul_f32_e32 v94, v162, v166
	v_min_f32_e32 v162, 0x42a00000, v137
	v_mul_f32_e32 v162, 0x3fb8aa3b, v162
	v_cmp_lt_i32_e32 vcc, v183, v88
	v_exp_f32_e32 v162, v162
	v_mul_f32_e32 v202, v68, v93
	v_cndmask_b32_e32 v94, 1.0, v94, vcc
	v_mul_f32_e32 v221, v94, v98
	v_mul_f32_e32 v222, v164, v221
	v_mul_f32_e32 v183, v100, v222
	v_add_f32_e32 v98, 1.0, v162
	v_min_f32_e32 v100, 0x42a00000, v136
	v_rcp_f32_e32 v98, v98
	v_mul_f32_e32 v100, 0x3fb8aa3b, v100
	v_exp_f32_e32 v100, v100
	v_cndmask_b32_e32 v220, 0, v166, vcc
	v_cmp_lt_i32_e32 vcc, v184, v88
	v_min_f32_e32 v164, 0x42a00000, v135
	v_mul_f32_e32 v164, 0x3fb8aa3b, v164
	v_cndmask_b32_e32 v184, 0, v98, vcc
	v_mul_f32_e32 v98, v162, v98
	v_cndmask_b32_e32 v162, 1.0, v98, vcc
	v_add_f32_e32 v98, 1.0, v100
	v_min_f32_e32 v166, 0x42a00000, v134
	v_rcp_f32_e32 v98, v98
	v_exp_f32_e32 v164, v164
	v_mul_f32_e32 v166, 0x3fb8aa3b, v166
	v_exp_f32_e32 v166, v166
	v_cmp_lt_i32_e32 vcc, v185, v88
	v_min_f32_e32 v68, 0x42a00000, v144
	v_exp_f32_e32 v66, v66
	v_cndmask_b32_e32 v185, 0, v98, vcc
	v_mul_f32_e32 v98, v100, v98
	v_add_f32_e32 v100, 1.0, v164
	v_rcp_f32_e32 v100, v100
	v_add_f32_e32 v168, 1.0, v166
	v_rcp_f32_e32 v168, v168
	v_cndmask_b32_e32 v167, 1.0, v98, vcc
	v_cmp_lt_i32_e32 vcc, v187, v88
	v_mul_f32_e32 v68, 0x3fb8aa3b, v68
	v_exp_f32_e32 v68, v68
	v_cndmask_b32_e32 v98, 0, v100, vcc
	v_mul_f32_e32 v100, v164, v100
	v_cndmask_b32_e32 v164, 1.0, v100, vcc
	v_mul_f32_e32 v100, v166, v168
	v_min_f32_e32 v166, 0x42a00000, v132
	v_mul_f32_e32 v166, 0x3fb8aa3b, v166
	v_cmp_lt_i32_e32 vcc, v199, v88
	v_exp_f32_e32 v166, v166
	v_mul_f32_e32 v93, v64, v93
	v_cndmask_b32_e32 v100, 1.0, v100, vcc
	v_mul_f32_e32 v199, v100, v164
	v_mul_f32_e32 v223, v167, v199
	v_mul_f32_e32 v224, v162, v223
	v_add_f32_e32 v162, 1.0, v166
	v_min_f32_e32 v164, 0x42a00000, v133
	v_rcp_f32_e32 v162, v162
	v_mul_f32_e32 v164, 0x3fb8aa3b, v164
	v_exp_f32_e32 v164, v164
	v_cndmask_b32_e32 v187, 0, v168, vcc
	v_cmp_lt_i32_e32 vcc, v203, v88
	v_add_f32_e32 v64, 1.0, v66
	v_min_f32_e32 v70, 0x42a00000, v142
	v_cndmask_b32_e32 v203, 0, v162, vcc
	v_mul_f32_e32 v162, v166, v162
	v_min_f32_e32 v166, 0x42a00000, v131
	v_cndmask_b32_e32 v167, 1.0, v162, vcc
	v_add_f32_e32 v162, 1.0, v164
	v_mul_f32_e32 v166, 0x3fb8aa3b, v166
	v_rcp_f32_e32 v72, v64
	v_add_f32_e32 v64, 1.0, v68
	v_rcp_f32_e32 v162, v162
	v_exp_f32_e32 v166, v166
	v_min_f32_e32 v168, 0x42a00000, v130
	v_mul_f32_e32 v70, 0x3fb8aa3b, v70
	v_rcp_f32_e32 v74, v64
	v_min_f32_e32 v64, 0x42a00000, v143
	v_mul_f32_e32 v168, 0x3fb8aa3b, v168
	v_exp_f32_e32 v70, v70
	v_mul_f32_e32 v64, 0x3fb8aa3b, v64
	v_exp_f32_e32 v168, v168
	v_exp_f32_e32 v64, v64
	v_cmp_lt_i32_e32 vcc, v205, v88
	v_add_f32_e32 v76, 1.0, v70
	v_add_f32_e32 v169, 1.0, v168
	v_cndmask_b32_e32 v205, 0, v162, vcc
	v_mul_f32_e32 v162, v164, v162
	v_add_f32_e32 v164, 1.0, v166
	v_rcp_f32_e32 v164, v164
	v_add_f32_e32 v79, 1.0, v71
	v_rcp_f32_e32 v78, v76
	v_add_f32_e32 v76, 1.0, v64
	v_rcp_f32_e32 v169, v169
	v_rcp_f32_e32 v79, v79
	v_rcp_f32_e32 v76, v76
	v_cndmask_b32_e32 v180, 1.0, v162, vcc
	v_cmp_lt_i32_e32 vcc, v207, v88
	v_pk_mul_f32 v[70:71], v[70:71], v[78:79]
	v_pk_mul_f32 v[64:65], v[64:65], v[76:77]
	v_cndmask_b32_e32 v162, 0, v164, vcc
	v_mul_f32_e32 v164, v166, v164
	v_cndmask_b32_e32 v166, 1.0, v164, vcc
	v_cmp_lt_i32_e32 vcc, v218, v88
	v_mul_f32_e32 v164, v168, v169
	v_or_b32_e32 v168, 3, v178
	v_cndmask_b32_e32 v207, 0, v169, vcc
	v_or_b32_e32 v169, 2, v178
	v_cndmask_b32_e32 v164, 1.0, v164, vcc
	v_cmp_lt_i32_e64 s[22:23], v169, v85
	v_cmp_lt_i32_e64 s[24:25], v168, v85
	v_mul_f32_e32 v218, v164, v166
	v_cmp_lt_i32_e64 s[20:21], v179, v85
	v_cndmask_b32_e64 v166, 0, v77, s[22:23]
	v_cndmask_b32_e64 v227, 0, v79, s[24:25]
	v_pk_mul_f32 v[68:69], v[68:69], v[74:75]
	v_cndmask_b32_e64 v71, 1.0, v71, s[24:25]
	v_cmp_lt_i32_e64 s[24:25], v169, v88
	v_cndmask_b32_e64 v169, 1.0, v65, s[22:23]
	v_cmp_lt_i32_e64 s[22:23], v168, v88
	v_cmp_lt_i32_e32 vcc, v178, v85
	v_cndmask_b32_e64 v226, 0, v75, s[20:21]
	v_pk_mul_f32 v[66:67], v[66:67], v[72:73]
	v_cndmask_b32_e64 v69, 1.0, v69, s[20:21]
	v_cmp_lt_i32_e64 s[20:21], v179, v88
	v_cndmask_b32_e64 v70, 1.0, v70, s[24:25]
	v_cndmask_b32_e64 v168, 1.0, v64, s[22:23]
	v_cndmask_b32_e32 v225, 0, v73, vcc
	v_cndmask_b32_e32 v67, 1.0, v67, vcc
	v_cmp_lt_i32_e32 vcc, v178, v88
	v_cndmask_b32_e64 v68, 1.0, v68, s[20:21]
	v_pk_mul_f32 v[170:171], v[70:71], v[168:169]
	v_cndmask_b32_e32 v66, 1.0, v66, vcc
	v_pk_mul_f32 v[172:173], v[68:69], v[170:171]
	v_mul_f32_e32 v228, v180, v218
	v_pk_mul_f32 v[174:175], v[66:67], v[172:173]
	ds_bpermute_b32 v177, v241, v175
	ds_bpermute_b32 v179, v242, v175
	ds_bpermute_b32 v181, v243, v175
	v_pk_mul_f32 v[96:97], v[96:97], v[96:97] op_sel:[0,1] op_sel_hi:[1,0]
	v_mul_f32_e32 v182, v167, v228
	s_waitcnt lgkmcnt(2)
	v_cndmask_b32_e64 v64, 1.0, v177, s[14:15]
	s_waitcnt lgkmcnt(1)
	v_cndmask_b32_e64 v65, 1.0, v179, s[16:17]
	v_mul_f32_e32 v64, v64, v65
	s_waitcnt lgkmcnt(0)
	v_cndmask_b32_e64 v65, 1.0, v181, s[18:19]
	v_mul_f32_e32 v167, v65, v64
	v_pk_mov_b32 v[64:65], v[70:71], v[96:97] op_sel:[1,0]
	v_mul_f32_e32 v66, v225, v173
	v_mul_f32_e32 v67, v226, v171
	v_pk_mul_f32 v[64:65], v[166:167], v[64:65]
	ds_bpermute_b32 v178, v242, v174
	v_mul_f32_e32 v66, v66, v65
	v_mul_f32_e32 v67, v67, v65
	v_mul_f32_e32 v64, v64, v65
	v_mul_f32_e32 v65, v227, v65
	v_cvt_pk_bf16_f32 v68, v66, v67
	v_cvt_pk_bf16_f32 v69, v64, v65
	v_cvt_pk_bf16_f32 v70, v95, v163
	v_cvt_pk_bf16_f32 v71, v165, v176
	ds_bpermute_b32 v176, v241, v174
	ds_bpermute_b32 v180, v243, v174
	ds_bpermute_b32 v75, v241, v183
	ds_bpermute_b32 v77, v242, v183
	ds_bpermute_b32 v79, v243, v183
	v_cndmask_b32_e64 v97, 0, v74, s[20:21]
	s_waitcnt lgkmcnt(4)
; __device__ __forceinline__ float fexp(float x) { return __builtin_amdgcn_exp2f(x * 1.44269504f); }
; __device__ __forceinline__ unsigned pack2(float a, float b) { unsigned r; asm volatile("v_cvt_pk_bf16_f32 %0, %1, %2" : "=v"(r) : "v"(a), "v"(b)); return r; }
; __device__ __forceinline__ void item_attn(const Params& p, int l, int aidx) {
;     ...
;             float f[4];
; #pragma unroll
;             for (int j = 0; j < 4; ++j) {
;               const float e = fexp(fminf(-z[m][n][j], 80.f));
;               const float sg = __builtin_amdgcn_rcpf(1.f + e);
;               if (decltype(MASKED)::value) {
;                 const bool ok = (kt * 64 + m * 16 + fq * 4 + j) < qpos;
;                 wgt[m][j] = ok ? sg : 0.f;
;                 f[j] = ok ? e * sg : 1.f;
;               } else { wgt[m][j] = sg; f[j] = e * sg; }
;             }
;             excl[m][3] = 1.f; excl[m][2] = f[3]; excl[m][1] = f[3] * f[2]; excl[m][0] = excl[m][1] * f[1];
;             const float G = excl[m][0] * f[0];
;             const float g1 = __shfl_xor(G, 16), g2 = __shfl_xor(G, 32), g3 = __shfl_xor(G, 48);
;             later[m] = ((fq ^ 1) > fq ? g1 : 1.f) * ((fq ^ 2) > fq ? g2 : 1.f) * ((fq ^ 3) > fq ? g3 : 1.f);
;             TT[m] = (G * g1) * (g2 * g3);
;           }
;           float lm[4]; lm[3] = carry[n]; lm[2] = lm[3] * TT[3]; lm[1] = lm[2] * TT[2]; lm[0] = lm[1] * TT[1];
; #pragma unroll
;           for (int m = 0; m < 4; ++m) {
;             const float base = later[m] * lm[m];
;             float pv[4];
; #pragma unroll
;             for (int j = 0; j < 4; ++j) pv[j] = wgt[m][j] * excl[m][j] * base;
;             pk[m][n][0] = pack2(pv[0], pv[1]); pk[m][n][1] = pack2(pv[2], pv[3]);
;           }
;           carry[n] = lm[0] * TT[0];
	v_cndmask_b32_e64 v73, 1.0, v176, s[14:15]
	v_cndmask_b32_e64 v74, 1.0, v178, s[16:17]
	v_mul_f32_e32 v73, v73, v74
	s_waitcnt lgkmcnt(3)
	v_cndmask_b32_e64 v74, 1.0, v180, s[18:19]
	v_cvt_pk_bf16_f32 v64, v99, v101
	v_cndmask_b32_e64 v101, 0, v76, s[22:23]
	v_mul_f32_e32 v73, v74, v73
	s_waitcnt lgkmcnt(2)
	v_cndmask_b32_e64 v74, 1.0, v75, s[14:15]
	s_waitcnt lgkmcnt(1)
	v_cndmask_b32_e64 v76, 1.0, v77, s[16:17]
	v_mul_f32_e32 v74, v74, v76
	s_waitcnt lgkmcnt(0)
	v_cndmask_b32_e64 v76, 1.0, v79, s[18:19]
	v_cvt_pk_bf16_f32 v65, v186, v200
	v_cvt_pk_bf16_f32 v66, v201, v202
	v_cvt_pk_bf16_f32 v67, v204, v93
	v_mul_f32_e32 v93, v76, v74
	ds_bpermute_b32 v163, v241, v224
	ds_bpermute_b32 v74, v242, v224
	v_cndmask_b32_e32 v95, 0, v72, vcc
	v_cndmask_b32_e64 v72, 0, v78, s[24:25]
	ds_bpermute_b32 v78, v243, v224
	v_pk_mul_f32 v[166:167], v[174:175], v[176:177]
	v_mul_f32_e32 v76, v183, v75
	ds_bpermute_b32 v183, v242, v182
	ds_bpermute_b32 v176, v241, v182
	ds_bpermute_b32 v177, v243, v182
	v_pk_mul_f32 v[174:175], v[178:179], v[180:181]
	s_waitcnt lgkmcnt(5)
	v_cndmask_b32_e64 v75, 1.0, v163, s[14:15]
	v_pk_mul_f32 v[166:167], v[166:167], v[174:175]
	v_mul_f32_e32 v174, v77, v79
	s_waitcnt lgkmcnt(4)
	v_cndmask_b32_e64 v77, 1.0, v74, s[16:17]
	v_mul_f32_e32 v75, v75, v77
	s_waitcnt lgkmcnt(3)
	v_cndmask_b32_e64 v77, 1.0, v78, s[18:19]
	v_mul_f32_e32 v99, v77, v75
	s_waitcnt lgkmcnt(2)
	v_cndmask_b32_e64 v75, 1.0, v183, s[16:17]
	s_waitcnt lgkmcnt(1)
	v_cndmask_b32_e64 v77, 1.0, v176, s[14:15]
	v_mul_f32_e32 v75, v77, v75
	s_waitcnt lgkmcnt(0)
	v_cndmask_b32_e64 v77, 1.0, v177, s[18:19]
	v_pk_mul_f32 v[176:177], v[182:183], v[176:177]
	v_mul_f32_e32 v165, v77, v75
	v_mov_b32_e32 v75, v176
	v_mov_b32_e32 v79, v177
	v_mul_f32_e32 v178, v224, v163
	v_pk_mul_f32 v[74:75], v[74:75], v[78:79]
	v_mov_b32_e32 v179, v90
	v_pk_mul_f32 v[78:79], v[178:179], v[74:75]
	v_mov_b32_e32 v163, v90
	v_mov_b32_e32 v77, v78
	v_mov_b32_e32 v175, v79
	v_pk_mul_f32 v[74:75], v[76:77], v[174:175]
	v_mul_f32_e32 v76, v97, v170
	v_pk_mul_f32 v[174:175], v[74:75], v[74:75] op_sel:[0,1] op_sel_hi:[1,0]
	v_mul_f32_e32 v74, v95, v172
	v_mov_b32_e32 v169, v174
	v_pk_mul_f32 v[72:73], v[72:73], v[168:169]
	v_mov_b32_e32 v95, v75
	v_mul_f32_e32 v74, v74, v73
	v_mul_f32_e32 v76, v76, v73
	v_mul_f32_e32 v77, v72, v73
	v_mul_f32_e32 v73, v101, v73
	v_cvt_pk_bf16_f32 v72, v74, v76
	v_cvt_pk_bf16_f32 v73, v77, v73
	v_mul_f32_e32 v76, v206, v222
	v_mul_f32_e32 v77, v219, v221
	v_pk_mul_f32 v[74:75], v[92:93], v[94:95]
	v_mov_b32_e32 v101, v79
	v_mul_f32_e32 v76, v76, v75
	v_mul_f32_e32 v77, v77, v75
	v_mul_f32_e32 v78, v74, v75
	v_mul_f32_e32 v75, v220, v75
	v_cvt_pk_bf16_f32 v74, v76, v77
	v_cvt_pk_bf16_f32 v75, v78, v75
	v_mul_f32_e32 v78, v184, v223
	v_mul_f32_e32 v92, v185, v199
	v_pk_mul_f32 v[76:77], v[98:99], v[100:101]
	v_mul_f32_e32 v93, v205, v218
	v_mul_f32_e32 v78, v78, v77
	v_mul_f32_e32 v79, v92, v77
	v_mul_f32_e32 v92, v76, v77
	v_mul_f32_e32 v77, v187, v77
	v_cvt_pk_bf16_f32 v76, v78, v79
	v_cvt_pk_bf16_f32 v77, v92, v77
	v_mul_f32_e32 v92, v203, v228
	v_pk_mul_f32 v[78:79], v[162:163], v[164:165]
	v_mov_b32_e32 v175, v96
	v_mul_f32_e32 v92, v92, v79
	v_mul_f32_e32 v93, v93, v79
	v_mul_f32_e32 v94, v78, v79
	v_mul_f32_e32 v79, v207, v79
	v_cvt_pk_bf16_f32 v78, v92, v93
	v_cvt_pk_bf16_f32 v79, v94, v79
	v_pk_mul_f32 v[92:93], v[166:167], v[174:175]
	s_mov_b64 s[0:1], 0
.LBB0_691:
	s_andn2_b64 vcc, exec, s[0:1]
	s_cbranch_vccnz .LBB0_693
	v_min_f32_e32 v64, 0x42a00000, v160
	v_mul_f32_e32 v64, 0x3fb8aa3b, v64
	v_exp_f32_e32 v69, v64
	v_min_f32_e32 v64, 0x42a00000, v161
	v_min_f32_e32 v66, 0x42a00000, v158
	v_mul_f32_e32 v64, 0x3fb8aa3b, v64
	v_min_f32_e32 v65, 0x42a00000, v159
	v_mul_f32_e32 v66, 0x3fb8aa3b, v66
	v_exp_f32_e32 v67, v64
	v_mul_f32_e32 v65, 0x3fb8aa3b, v65
	v_exp_f32_e32 v71, v66
	v_min_f32_e32 v66, 0x42a00000, v157
	v_exp_f32_e32 v65, v65
	v_mul_f32_e32 v66, 0x3fb8aa3b, v66
	v_exp_f32_e32 v92, v66
	v_min_f32_e32 v66, 0x42a00000, v156
	v_add_f32_e32 v64, 1.0, v69
	v_mul_f32_e32 v66, 0x3fb8aa3b, v66
	v_rcp_f32_e32 v77, v64
	v_add_f32_e32 v64, 1.0, v67
	v_exp_f32_e32 v66, v66
	v_rcp_f32_e32 v79, v64
	v_add_f32_e32 v64, 1.0, v65
	v_rcp_f32_e32 v73, v64
	v_add_f32_e32 v64, 1.0, v71
	v_min_f32_e32 v68, 0x42a00000, v154
	v_rcp_f32_e32 v75, v64
	v_add_f32_e32 v64, 1.0, v92
	v_mul_f32_e32 v68, 0x3fb8aa3b, v68
	v_rcp_f32_e32 v94, v64
	v_add_f32_e32 v64, 1.0, v66
	v_exp_f32_e32 v97, v68
	v_min_f32_e32 v68, 0x42a00000, v155
	v_rcp_f32_e32 v64, v64
	v_mul_f32_e32 v68, 0x3fb8aa3b, v68
	v_exp_f32_e32 v96, v68
	v_min_f32_e32 v68, 0x42a00000, v151
	v_mul_f32_e32 v93, v66, v64
	v_add_f32_e32 v66, 1.0, v97
	v_rcp_f32_e32 v99, v66
	v_add_f32_e32 v66, 1.0, v96
	v_rcp_f32_e32 v98, v66
	v_min_f32_e32 v66, 0x42a00000, v153
	v_mul_f32_e32 v66, 0x3fb8aa3b, v66
	v_exp_f32_e32 v66, v66
	v_mul_f32_e32 v68, 0x3fb8aa3b, v68
	v_min_f32_e32 v70, 0x42a00000, v152
	v_exp_f32_e32 v100, v68
	v_add_f32_e32 v68, 1.0, v66
	v_mul_f32_e32 v70, 0x3fb8aa3b, v70
	v_rcp_f32_e32 v68, v68
	v_exp_f32_e32 v151, v70
	v_min_f32_e32 v72, 0x42a00000, v148
	v_add_f32_e32 v70, 1.0, v100
	v_mul_f32_e32 v101, v66, v68
	v_add_f32_e32 v66, 1.0, v151
	v_rcp_f32_e32 v155, v66
	v_min_f32_e32 v66, 0x42a00000, v150
	v_mul_f32_e32 v66, 0x3fb8aa3b, v66
	v_exp_f32_e32 v150, v66
	v_min_f32_e32 v66, 0x42a00000, v149
	v_mul_f32_e32 v66, 0x3fb8aa3b, v66
	v_exp_f32_e32 v66, v66
	v_mul_f32_e32 v72, 0x3fb8aa3b, v72
	v_rcp_f32_e32 v152, v70
	v_min_f32_e32 v70, 0x42a00000, v147
	v_exp_f32_e32 v147, v72
	v_min_f32_e32 v72, 0x42a00000, v146
	v_mul_f32_e32 v72, 0x3fb8aa3b, v72
	v_mul_f32_e32 v70, 0x3fb8aa3b, v70
	v_exp_f32_e32 v146, v72
	v_exp_f32_e32 v156, v70
	v_add_f32_e32 v70, 1.0, v66
	v_rcp_f32_e32 v70, v70
	v_add_f32_e32 v72, 1.0, v147
	v_rcp_f32_e32 v149, v72
	v_add_f32_e32 v72, 1.0, v146
	v_rcp_f32_e32 v148, v72
	v_mul_f32_e32 v157, v66, v70
	v_add_f32_e32 v66, 1.0, v150
	v_add_f32_e32 v72, 1.0, v156
	v_rcp_f32_e32 v154, v66
	v_rcp_f32_e32 v158, v72
	v_pk_mul_f32 v[146:147], v[146:147], v[148:149]
	v_pk_mul_f32 v[96:97], v[96:97], v[98:99]
	v_pk_mul_f32 v[160:161], v[146:147], v[146:147] op_sel:[0,1] op_sel_hi:[1,0]
	v_pk_mul_f32 v[150:151], v[150:151], v[154:155]
	v_mov_b32_e32 v159, v160
	v_pk_mul_f32 v[156:157], v[156:157], v[158:159]
	v_pk_mul_f32 v[166:167], v[150:151], v[150:151] op_sel:[0,1] op_sel_hi:[1,0]
	v_pk_mul_f32 v[162:163], v[156:157], v[156:157] op_sel:[0,1] op_sel_hi:[1,0]
	v_mov_b32_e32 v153, v166
	ds_bpermute_b32 v163, v242, v162
	ds_bpermute_b32 v164, v241, v162
	ds_bpermute_b32 v165, v243, v162
	v_pk_mul_f32 v[100:101], v[100:101], v[152:153]
	v_mul_f32_e32 v68, v68, v166
	v_mul_f32_e32 v74, v100, v101
	ds_bpermute_b32 v76, v241, v74
	ds_bpermute_b32 v168, v242, v74
	ds_bpermute_b32 v170, v243, v74
	s_waitcnt lgkmcnt(5)
; __device__ __forceinline__ float fexp(float x) { return __builtin_amdgcn_exp2f(x * 1.44269504f); }
; __device__ __forceinline__ unsigned pack2(float a, float b) { unsigned r; asm volatile("v_cvt_pk_bf16_f32 %0, %1, %2" : "=v"(r) : "v"(a), "v"(b)); return r; }
; __device__ __forceinline__ void item_attn(const Params& p, int l, int aidx) {
;     ...
;             float f[4];
; #pragma unroll
;             for (int j = 0; j < 4; ++j) {
;               const float e = fexp(fminf(-z[m][n][j], 80.f));
;               const float sg = __builtin_amdgcn_rcpf(1.f + e);
;               if (decltype(MASKED)::value) {
;                 const bool ok = (kt * 64 + m * 16 + fq * 4 + j) < qpos;
;                 wgt[m][j] = ok ? sg : 0.f;
;                 f[j] = ok ? e * sg : 1.f;
;               } else { wgt[m][j] = sg; f[j] = e * sg; }
;             }
;             excl[m][3] = 1.f; excl[m][2] = f[3]; excl[m][1] = f[3] * f[2]; excl[m][0] = excl[m][1] * f[1];
;             const float G = excl[m][0] * f[0];
;             const float g1 = __shfl_xor(G, 16), g2 = __shfl_xor(G, 32), g3 = __shfl_xor(G, 48);
;             later[m] = ((fq ^ 1) > fq ? g1 : 1.f) * ((fq ^ 2) > fq ? g2 : 1.f) * ((fq ^ 3) > fq ? g3 : 1.f);
;             TT[m] = (G * g1) * (g2 * g3);
;           }
;           float lm[4]; lm[3] = carry[n]; lm[2] = lm[3] * TT[3]; lm[1] = lm[2] * TT[2]; lm[0] = lm[1] * TT[1];
; #pragma unroll
;           for (int m = 0; m < 4; ++m) {
;             const float base = later[m] * lm[m];
;             float pv[4];
; #pragma unroll
;             for (int j = 0; j < 4; ++j) pv[j] = wgt[m][j] * excl[m][j] * base;
;             pk[m][n][0] = pack2(pv[0], pv[1]); pk[m][n][1] = pack2(pv[2], pv[3]);
;           }
;           carry[n] = lm[0] * TT[0];
	v_cndmask_b32_e64 v66, 1.0, v163, s[16:17]
	s_waitcnt lgkmcnt(3)
	v_pk_mul_f32 v[162:163], v[162:163], v[164:165]
	v_cndmask_b32_e64 v72, 1.0, v164, s[14:15]
	v_mov_b32_e32 v169, v162
	v_mov_b32_e32 v171, v163
	v_mul_f32_e32 v66, v72, v66
	v_cndmask_b32_e64 v72, 1.0, v165, s[18:19]
	s_waitcnt lgkmcnt(2)
	v_mul_f32_e32 v164, v74, v76
	s_waitcnt lgkmcnt(0)
	v_pk_mul_f32 v[162:163], v[168:169], v[170:171]
	v_mov_b32_e32 v165, v91
	v_pk_mul_f32 v[162:163], v[164:165], v[162:163]
	v_pk_mul_f32 v[164:165], v[96:97], v[96:97] op_sel:[0,1] op_sel_hi:[1,0]
	v_mul_f32_e32 v147, v72, v66
	v_cndmask_b32_e64 v66, 1.0, v76, s[14:15]
	v_cndmask_b32_e64 v72, 1.0, v168, s[16:17]
	v_mov_b32_e32 v95, v164
	v_mul_f32_e32 v66, v66, v72
	v_cndmask_b32_e64 v72, 1.0, v170, s[18:19]
	v_pk_mul_f32 v[92:93], v[92:93], v[94:95]
	v_mul_f32_e32 v151, v72, v66
	v_mul_f32_e32 v66, v92, v93
	ds_bpermute_b32 v72, v241, v66
	ds_bpermute_b32 v74, v242, v66
	ds_bpermute_b32 v78, v243, v66
	v_mul_f32_e32 v76, v152, v101
	v_mov_b32_e32 v101, v162
	s_waitcnt lgkmcnt(2)
	v_cndmask_b32_e64 v92, 1.0, v72, s[14:15]
	s_waitcnt lgkmcnt(1)
	v_cndmask_b32_e64 v95, 1.0, v74, s[16:17]
	v_mul_f32_e32 v100, v66, v72
	s_waitcnt lgkmcnt(0)
	v_mul_f32_e32 v152, v74, v78
	v_mov_b32_e32 v153, v163
	v_mul_f32_e32 v92, v92, v95
	v_cndmask_b32_e64 v95, 1.0, v78, s[18:19]
	v_pk_mul_f32 v[100:101], v[100:101], v[152:153]
	v_mul_f32_e32 v97, v95, v92
	v_mul_f32_e32 v66, v94, v93
	v_mov_b32_e32 v92, v99
	v_mov_b32_e32 v93, v101
	v_mul_f32_e32 v64, v64, v164
	v_pk_mul_f32 v[92:93], v[92:93], v[96:97]
	v_mov_b32_e32 v162, v155
	v_mul_f32_e32 v97, v66, v93
	v_mul_f32_e32 v156, v64, v93
	v_mul_f32_e32 v161, v92, v93
	v_mul_f32_e32 v164, v98, v93
	v_pk_mul_f32 v[92:93], v[162:163], v[150:151]
	v_mul_f32_e32 v64, v158, v157
	v_mul_f32_e32 v162, v76, v93
	v_mul_f32_e32 v163, v68, v93
	v_mul_f32_e32 v165, v92, v93
	v_mul_f32_e32 v166, v154, v93
	v_mov_b32_e32 v92, v149
	v_mov_b32_e32 v93, v91
	v_pk_mul_f32 v[92:93], v[92:93], v[146:147]
	v_min_f32_e32 v137, 0x42a00000, v137
	v_mul_f32_e32 v167, v64, v93
	v_mul_f32_e32 v64, v70, v160
	v_mul_f32_e32 v160, v64, v93
	v_min_f32_e32 v64, 0x42a00000, v145
	v_mul_f32_e32 v64, 0x3fb8aa3b, v64
	v_exp_f32_e32 v68, v64
	v_min_f32_e32 v64, 0x42a00000, v144
	v_mul_f32_e32 v168, v92, v93
	v_mul_f32_e32 v64, 0x3fb8aa3b, v64
	v_min_f32_e32 v92, 0x42a00000, v141
	v_exp_f32_e32 v66, v64
	v_add_f32_e32 v64, 1.0, v68
	v_mul_f32_e32 v92, 0x3fb8aa3b, v92
	v_rcp_f32_e32 v76, v64
	v_min_f32_e32 v64, 0x42a00000, v142
	v_exp_f32_e32 v94, v92
	v_min_f32_e32 v92, 0x42a00000, v140
	v_mul_f32_e32 v64, 0x3fb8aa3b, v64
	v_mul_f32_e32 v92, 0x3fb8aa3b, v92
	v_exp_f32_e32 v70, v64
	v_min_f32_e32 v64, 0x42a00000, v143
	v_exp_f32_e32 v92, v92
	v_mul_f32_e32 v64, 0x3fb8aa3b, v64
	v_exp_f32_e32 v64, v64
	v_mul_f32_e32 v169, v148, v93
	v_add_f32_e32 v93, 1.0, v94
	v_add_f32_e32 v72, 1.0, v66
	v_rcp_f32_e32 v96, v93
	v_add_f32_e32 v93, 1.0, v92
	v_rcp_f32_e32 v78, v72
	v_add_f32_e32 v72, 1.0, v70
	v_rcp_f32_e32 v170, v93
	v_min_f32_e32 v93, 0x42a00000, v139
	v_min_f32_e32 v136, 0x42a00000, v136
	v_rcp_f32_e32 v74, v72
	v_add_f32_e32 v72, 1.0, v64
	v_mul_f32_e32 v93, 0x3fb8aa3b, v93
	v_mul_f32_e32 v137, 0x3fb8aa3b, v137
	v_mul_f32_e32 v136, 0x3fb8aa3b, v136
	v_rcp_f32_e32 v72, v72
	v_exp_f32_e32 v99, v93
	v_min_f32_e32 v93, 0x42a00000, v138
	v_exp_f32_e32 v138, v137
	v_exp_f32_e32 v137, v136
	v_min_f32_e32 v135, 0x42a00000, v135
	v_mul_f32_e32 v135, 0x3fb8aa3b, v135
	v_min_f32_e32 v134, 0x42a00000, v134
	v_add_f32_e32 v139, 1.0, v137
	v_pk_mul_f32 v[70:71], v[70:71], v[74:75]
	v_pk_mul_f32 v[146:147], v[64:65], v[72:73]
	v_rcp_f32_e32 v171, v139
	v_exp_f32_e32 v135, v135
	v_mul_f32_e32 v134, 0x3fb8aa3b, v134
	v_min_f32_e32 v133, 0x42a00000, v133
	v_pk_mul_f32 v[66:67], v[66:67], v[78:79]
	v_pk_mul_f32 v[148:149], v[70:71], v[146:147]
	v_exp_f32_e32 v134, v134
	v_mul_f32_e32 v133, 0x3fb8aa3b, v133
	v_min_f32_e32 v132, 0x42a00000, v132
	v_min_f32_e32 v130, 0x42a00000, v130
	v_pk_mul_f32 v[68:69], v[68:69], v[76:77]
	v_pk_mul_f32 v[150:151], v[66:67], v[148:149]
	v_exp_f32_e32 v133, v133
	v_mul_f32_e32 v132, 0x3fb8aa3b, v132
	v_min_f32_e32 v131, 0x42a00000, v131
	v_mul_f32_e32 v130, 0x3fb8aa3b, v130
	v_pk_mul_f32 v[152:153], v[68:69], v[150:151]
	v_exp_f32_e32 v132, v132
	v_mul_f32_e32 v131, 0x3fb8aa3b, v131
	v_exp_f32_e32 v130, v130
	ds_bpermute_b32 v155, v241, v153
	ds_bpermute_b32 v157, v242, v153
	v_mul_f32_e32 v139, v137, v171
	v_add_f32_e32 v137, 1.0, v135
	v_exp_f32_e32 v131, v131
	ds_bpermute_b32 v159, v243, v153
	v_rcp_f32_e32 v141, v137
	v_add_f32_e32 v137, 1.0, v134
	v_rcp_f32_e32 v140, v137
	v_add_f32_e32 v137, 1.0, v133
	v_rcp_f32_e32 v172, v137
	v_add_f32_e32 v137, 1.0, v132
	v_add_f32_e32 v64, 1.0, v130
	v_rcp_f32_e32 v142, v137
	v_add_f32_e32 v137, 1.0, v131
	v_rcp_f32_e32 v144, v64
	s_waitcnt lgkmcnt(2)
	v_cndmask_b32_e64 v64, 1.0, v155, s[14:15]
	s_waitcnt lgkmcnt(1)
	v_cndmask_b32_e64 v65, 1.0, v157, s[16:17]
	v_rcp_f32_e32 v145, v137
	v_mul_f32_e32 v64, v64, v65
	s_waitcnt lgkmcnt(0)
; __device__ __forceinline__ float fexp(float x) { return __builtin_amdgcn_exp2f(x * 1.44269504f); }
; __device__ __forceinline__ unsigned pack2(float a, float b) { unsigned r; asm volatile("v_cvt_pk_bf16_f32 %0, %1, %2" : "=v"(r) : "v"(a), "v"(b)); return r; }
; __device__ __forceinline__ void item_attn(const Params& p, int l, int aidx) {
;     ...
;             float f[4];
; #pragma unroll
;             for (int j = 0; j < 4; ++j) {
;               const float e = fexp(fminf(-z[m][n][j], 80.f));
;               const float sg = __builtin_amdgcn_rcpf(1.f + e);
;               if (decltype(MASKED)::value) {
;                 const bool ok = (kt * 64 + m * 16 + fq * 4 + j) < qpos;
;                 wgt[m][j] = ok ? sg : 0.f;
;                 f[j] = ok ? e * sg : 1.f;
;               } else { wgt[m][j] = sg; f[j] = e * sg; }
;             }
;             excl[m][3] = 1.f; excl[m][2] = f[3]; excl[m][1] = f[3] * f[2]; excl[m][0] = excl[m][1] * f[1];
;             const float G = excl[m][0] * f[0];
;             const float g1 = __shfl_xor(G, 16), g2 = __shfl_xor(G, 32), g3 = __shfl_xor(G, 48);
;             later[m] = ((fq ^ 1) > fq ? g1 : 1.f) * ((fq ^ 2) > fq ? g2 : 1.f) * ((fq ^ 3) > fq ? g3 : 1.f);
;             TT[m] = (G * g1) * (g2 * g3);
;           }
;           float lm[4]; lm[3] = carry[n]; lm[2] = lm[3] * TT[3]; lm[1] = lm[2] * TT[2]; lm[0] = lm[1] * TT[1];
; #pragma unroll
;           for (int m = 0; m < 4; ++m) {
;             const float base = later[m] * lm[m];
;             float pv[4];
; #pragma unroll
;             for (int j = 0; j < 4; ++j) pv[j] = wgt[m][j] * excl[m][j] * base;
;             pk[m][n][0] = pack2(pv[0], pv[1]); pk[m][n][1] = pack2(pv[2], pv[3]);
;           }
;           carry[n] = lm[0] * TT[0];
	v_cndmask_b32_e64 v65, 1.0, v159, s[18:19]
	v_pk_mul_f32 v[100:101], v[100:101], v[100:101] op_sel:[0,1] op_sel_hi:[1,0]
	ds_bpermute_b32 v154, v241, v152
	v_mul_f32_e32 v65, v65, v64
	v_mov_b32_e32 v64, v73
	v_pk_mov_b32 v[66:67], v[70:71], v[100:101] op_sel:[1,0]
	v_mul_f32_e32 v68, v77, v151
	v_mul_f32_e32 v69, v79, v149
	v_pk_mul_f32 v[64:65], v[64:65], v[66:67]
	ds_bpermute_b32 v158, v243, v152
	v_mul_f32_e32 v66, v68, v65
	v_mul_f32_e32 v67, v69, v65
	v_mul_f32_e32 v64, v64, v65
	v_mul_f32_e32 v65, v75, v65
	v_cvt_pk_bf16_f32 v68, v66, v67
	v_cvt_pk_bf16_f32 v69, v64, v65
	v_cvt_pk_bf16_f32 v70, v97, v156
	ds_bpermute_b32 v156, v242, v152
	v_pk_mul_f32 v[130:131], v[130:131], v[144:145]
	s_waitcnt lgkmcnt(2)
	v_pk_mul_f32 v[152:153], v[152:153], v[154:155]
	v_cndmask_b32_e64 v73, 1.0, v154, s[14:15]
	v_pk_mul_f32 v[154:155], v[130:131], v[130:131] op_sel:[0,1] op_sel_hi:[1,0]
	v_mul_f32_e32 v133, v133, v172
	v_mov_b32_e32 v143, v154
	v_pk_mul_f32 v[132:133], v[132:133], v[142:143]
	v_cvt_pk_bf16_f32 v71, v161, v164
	v_cvt_pk_bf16_f32 v64, v162, v163
	v_cvt_pk_bf16_f32 v65, v165, v166
	v_cvt_pk_bf16_f32 v66, v167, v160
	s_waitcnt lgkmcnt(0)
	v_pk_mul_f32 v[160:161], v[156:157], v[158:159]
	v_cndmask_b32_e64 v75, 1.0, v156, s[16:17]
	v_pk_mul_f32 v[156:157], v[132:133], v[132:133] op_sel:[0,1] op_sel_hi:[1,0]
	v_mul_f32_e32 v73, v73, v75
	v_cndmask_b32_e64 v75, 1.0, v158, s[18:19]
	ds_bpermute_b32 v157, v242, v156
	ds_bpermute_b32 v158, v241, v156
	v_add_f32_e32 v136, 1.0, v138
	v_rcp_f32_e32 v136, v136
	v_mul_f32_e32 v75, v75, v73
	v_mul_f32_e32 v73, v76, v150
	s_waitcnt lgkmcnt(1)
	v_cndmask_b32_e64 v76, 1.0, v157, s[16:17]
	s_waitcnt lgkmcnt(0)
	v_cndmask_b32_e64 v77, 1.0, v158, s[14:15]
	v_mul_f32_e32 v93, 0x3fb8aa3b, v93
	v_mul_f32_e32 v97, v77, v76
	v_pk_mul_f32 v[76:77], v[134:135], v[140:141]
	v_exp_f32_e32 v98, v93
	v_mul_f32_e32 v101, v78, v148
	v_pk_mul_f32 v[78:79], v[76:77], v[76:77] op_sel:[0,1] op_sel_hi:[1,0]
	v_mul_f32_e32 v95, v92, v170
	v_mov_b32_e32 v137, v78
	v_pk_mul_f32 v[134:135], v[138:139], v[136:137]
	v_add_f32_e32 v92, 1.0, v99
	ds_bpermute_b32 v159, v243, v156
	v_mul_f32_e32 v79, v134, v135
	v_rcp_f32_e32 v93, v92
	v_add_f32_e32 v92, 1.0, v98
	ds_bpermute_b32 v132, v241, v79
	ds_bpermute_b32 v138, v242, v79
	v_rcp_f32_e32 v92, v92
	ds_bpermute_b32 v148, v243, v79
	s_waitcnt lgkmcnt(3)
	v_cndmask_b32_e64 v131, 1.0, v159, s[18:19]
	v_pk_mul_f32 v[150:151], v[156:157], v[158:159]
	v_mul_f32_e32 v131, v131, v97
	s_waitcnt lgkmcnt(2)
	v_cndmask_b32_e64 v77, 1.0, v132, s[14:15]
	s_waitcnt lgkmcnt(1)
	v_cndmask_b32_e64 v97, 1.0, v138, s[16:17]
	v_mov_b32_e32 v139, v150
	v_mov_b32_e32 v149, v151
	v_pk_mul_f32 v[98:99], v[98:99], v[92:93]
	v_mul_f32_e32 v77, v77, v97
	s_waitcnt lgkmcnt(0)
	v_cndmask_b32_e64 v97, 1.0, v148, s[18:19]
	v_pk_mul_f32 v[138:139], v[138:139], v[148:149]
	v_pk_mul_f32 v[148:149], v[98:99], v[98:99] op_sel:[0,1] op_sel_hi:[1,0]
	v_mul_f32_e32 v77, v97, v77
	v_mov_b32_e32 v97, v148
	v_pk_mul_f32 v[94:95], v[94:95], v[96:97]
	v_mul_f32_e32 v156, v79, v132
	v_mul_f32_e32 v79, v94, v95
	ds_bpermute_b32 v94, v241, v79
	ds_bpermute_b32 v97, v242, v79
	ds_bpermute_b32 v128, v243, v79
	v_mov_b32_e32 v157, v90
	v_mul_f32_e32 v132, v171, v78
	s_waitcnt lgkmcnt(2)
	v_cndmask_b32_e64 v78, 1.0, v94, s[14:15]
	s_waitcnt lgkmcnt(1)
	v_cndmask_b32_e64 v99, 1.0, v97, s[16:17]
	v_pk_mul_f32 v[138:139], v[156:157], v[138:139]
	v_mul_f32_e32 v78, v78, v99
	s_waitcnt lgkmcnt(0)
	v_cndmask_b32_e64 v99, 1.0, v128, s[18:19]
	v_mul_f32_e32 v99, v99, v78
	v_mul_f32_e32 v78, v79, v94
	v_mul_f32_e32 v128, v97, v128
	v_mov_b32_e32 v79, v138
	v_mov_b32_e32 v129, v139
	v_pk_mul_f32 v[78:79], v[78:79], v[128:129]
	v_mul_f32_e32 v96, v96, v95
	v_pk_mul_f32 v[94:95], v[78:79], v[78:79] op_sel:[0,1] op_sel_hi:[1,0]
	v_cvt_pk_bf16_f32 v67, v168, v169
	v_mul_f32_e32 v97, v170, v148
	v_mov_b32_e32 v147, v94
	v_pk_mul_f32 v[74:75], v[74:75], v[146:147]
	v_mov_b32_e32 v138, v141
	v_mul_f32_e32 v78, v101, v75
	v_mul_f32_e32 v73, v73, v75
	v_mul_f32_e32 v74, v74, v75
	v_mul_f32_e32 v75, v72, v75
	v_cvt_pk_bf16_f32 v72, v73, v78
	v_mov_b32_e32 v78, v93
	v_cvt_pk_bf16_f32 v73, v74, v75
	v_pk_mul_f32 v[74:75], v[78:79], v[98:99]
	v_mul_f32_e32 v127, v136, v135
	v_mul_f32_e32 v78, v96, v75
	v_mul_f32_e32 v79, v97, v75
	v_pk_mul_f32 v[76:77], v[138:139], v[76:77]
	v_mul_f32_e32 v93, v74, v75
	v_mul_f32_e32 v75, v92, v75
	v_cvt_pk_bf16_f32 v74, v78, v79
	v_mul_f32_e32 v78, v127, v77
	v_mul_f32_e32 v79, v132, v77
	v_cvt_pk_bf16_f32 v75, v93, v75
	v_mul_f32_e32 v92, v76, v77
	v_mul_f32_e32 v77, v140, v77
	v_cvt_pk_bf16_f32 v76, v78, v79
	v_pk_mov_b32 v[78:79], v[144:145], v[90:91] op_sel:[1,0]
	v_cvt_pk_bf16_f32 v77, v92, v77
	v_mul_f32_e32 v92, v142, v133
	v_pk_mul_f32 v[78:79], v[78:79], v[130:131]
	v_mul_f32_e32 v91, v172, v154
	v_pk_mul_f32 v[152:153], v[152:153], v[160:161]
	v_mul_f32_e32 v90, v92, v79
	v_mul_f32_e32 v91, v91, v79
	v_mul_f32_e32 v92, v78, v79
	v_mul_f32_e32 v79, v144, v79
	v_mov_b32_e32 v95, v100
	v_cvt_pk_bf16_f32 v78, v90, v91
	v_cvt_pk_bf16_f32 v79, v92, v79
	v_pk_mul_f32 v[92:93], v[152:153], v[94:95]

.Lattn_touch:
	v_readlane_b32 s100, v247, 13
	v_readlane_b32 s101, v247, 14
	s_add_i32 s99, s47, -1
	s_add_u32 s100, s100, s44
	s_addc_u32 s101, s101, s45
	v_min_i32_e32 v236, s99, v84
	v_min_i32_e32 v238, s99, v86
	v_ashrrev_i32_e32 v237, 31, v236
	v_ashrrev_i32_e32 v239, 31, v238
	v_lshl_add_u64 v[236:237], s[34:35], 0, v[236:237]
	v_lshl_add_u64 v[238:239], s[34:35], 0, v[238:239]
	v_lshlrev_b64 v[236:237], 10, v[236:237]
	v_lshlrev_b64 v[238:239], 10, v[238:239]
	v_lshl_add_u64 v[236:237], s[100:101], 0, v[236:237]
	v_lshl_add_u64 v[238:239], s[100:101], 0, v[238:239]
	global_load_dword v234, v[236:237], off
	global_load_dword v235, v[238:239], off
	s_cmp_lg_u32 s98, 0
	s_cbranch_scc0 .Lkv_skip
	v_readfirstlane_b32 s99, v188
	s_cmp_lt_u32 s99, 64
	s_cbranch_scc0 .Lkv_skip
	v_readfirstlane_b32 s99, v245
	s_sub_u32 s99, s99, 0x14a
	s_cmp_lt_u32 s99, 0x800
	s_cbranch_scc0 .Lkv_skip
	s_bfe_u32 s100, s99, 0x50003
	s_lshl_b32 s100, s100, 22
	s_lshr_b32 s101, s99, 8
	s_sub_i32 s101, 7, s101
	s_lshl_b32 s101, s101, 19
	s_add_i32 s100, s100, s101
	s_and_b32 s101, s99, 7
	s_lshl_b32 s101, s101, 8
	s_add_i32 s100, s100, s101
	s_add_i32 s100, s100, 0x40000
	v_readlane_b32 s99, v246, 17
	v_lshrrev_b32_e32 v236, 1, v215
	v_and_b32_e32 v237, 1, v215
	v_lshlrev_b32_e32 v236, 11, v236
	v_lshl_or_b32 v236, v237, 7, v236
	s_lshl_b32 s99, s99, 2
	s_add_u32 s100, s100, s99
	v_add_u32_e32 v236, s100, v236
	v_add_u32_e32 v237, 0x10000, v236
	v_add_u32_e32 v238, 0x20000, v236
	v_add_u32_e32 v239, 0x30000, v236
	v_readlane_b32 s100, v248, 8
	v_readlane_b32 s101, v248, 9
	s_nop 4
	global_load_dword v240, v236, s[100:101]
	global_load_dword v240, v237, s[100:101]
	global_load_dword v240, v238, s[100:101]
	global_load_dword v240, v239, s[100:101]
	v_readlane_b32 s100, v248, 6
	v_readlane_b32 s101, v248, 7
	s_nop 4
	global_load_dword v240, v236, s[100:101]
	global_load_dword v240, v237, s[100:101]
	global_load_dword v240, v238, s[100:101]
	global_load_dword v240, v239, s[100:101]

; __device__ __forceinline__ float fexp(float x) { return __builtin_amdgcn_exp2f(x * 1.44269504f); }
; __device__ __forceinline__ void item_attn(const Params& p, int l, int aidx) {
;     ...
;       for (int m = 0; m < 4; ++m) {
;         bf16x8 a0 = *reinterpret_cast<const bf16x8*>(Ks + (m * 16 + fr) * 72 + fq * 8);
;         bf16x8 a1 = *reinterpret_cast<const bf16x8*>(Ks + (m * 16 + fr) * 72 + 32 + fq * 8);
; #pragma unroll
;         for (int n = 0; n < 2; ++n) {
;           f32x4 zz = f32x4{0.f, 0.f, 0.f, 0.f};
;           zz = __builtin_amdgcn_mfma_f32_16x16x32_bf16(a0, qf[n][0], zz, 0, 0, 0);
;           zz = __builtin_amdgcn_mfma_f32_16x16x32_bf16(a1, qf[n][1], zz, 0, 0, 0);
;           z[m][n] = zz;
;         }
;       }
;       unsigned pk[4][2][2];
;       auto sb_weights = [&](auto MASKED) {
; #pragma unroll
;         for (int n = 0; n < 2; ++n) {
;           const int qpos = qpos0 + 32 * wid + 16 * n + fr;
;           float wgt[4][4], excl[4][4], later[4], TT[4];
; #pragma unroll
;           for (int m = 0; m < 4; ++m) {
;             float f[4];
; #pragma unroll
;             for (int j = 0; j < 4; ++j) {
;               const float e = fexp(fminf(-z[m][n][j], 80.f));
;               const float sg = __builtin_amdgcn_rcpf(1.f + e);
;               if (decltype(MASKED)::value) {
;                 const bool ok = (kt * 64 + m * 16 + fq * 4 + j) < qpos;
;                 wgt[m][j] = ok ? sg : 0.f;
;                 f[j] = ok ? e * sg : 1.f;
;               } else { wgt[m][j] = sg; f[j] = e * sg; }
;             }
;             excl[m][3] = 1.f; excl[m][2] = f[3]; excl[m][1] = f[3] * f[2]; excl[m][0] = excl[m][1] * f[1];
;             const float G = excl[m][0] * f[0];
;             const float g1 = __shfl_xor(G, 16), g2 = __shfl_xor(G, 32), g3 = __shfl_xor(G, 48);
;             later[m] = ((fq ^ 1) > fq ? g1 : 1.f) * ((fq ^ 2) > fq ? g2 : 1.f) * ((fq ^ 3) > fq ? g3 : 1.f);
;             TT[m] = (G * g1) * (g2 * g3);
;           }
.LBB0_760:
	s_andn2_b64 vcc, exec, s[4:5]
	s_mov_b64 s[0:1], -1
	s_cbranch_vccnz .LBB0_767
	s_cmp_ge_i32 s49, s51
	s_mov_b64 s[0:1], 0
	s_cbranch_scc1 .LBB0_767
	ds_read_b128 v[64:67], v118
	ds_read_b128 v[68:71], v118 offset:64
	s_nop 0
	s_nop 0
	s_nop 0
	s_waitcnt lgkmcnt(1)
	v_mfma_f32_16x16x32_bf16 v[72:75], v[64:67], v[4:7], 0
	s_nop 0
	s_add_i32 s0, s49, 63
	s_cmp_lt_i32 s0, s50
	v_mfma_f32_16x16x32_bf16 v[64:67], v[64:67], v[12:15], 0
	s_nop 0
	s_nop 0
	s_nop 0
	s_waitcnt lgkmcnt(0)
	v_mfma_f32_16x16x32_bf16 v[72:75], v[68:71], v[0:3], v[72:75]
	s_nop 0
	s_mov_b64 s[0:1], -1
	v_mfma_f32_16x16x32_bf16 v[64:67], v[68:71], v[8:11], v[64:67]
	ds_read_b128 v[68:71], v118 offset:2304
	ds_read_b128 v[76:79], v118 offset:2368
	s_nop 0
	s_nop 1
	s_nop 0
	s_waitcnt lgkmcnt(1)
	v_mfma_f32_16x16x32_bf16 v[92:95], v[68:71], v[4:7], 0
	v_pk_mul_f32 v[160:161], v[72:73], 1.0 op_sel_hi:[1,0] neg_lo:[1,0] neg_hi:[1,0]
	s_nop 0
	v_pk_mul_f32 v[158:159], v[74:75], 1.0 op_sel:[1,0] op_sel_hi:[0,0] neg_lo:[1,0] neg_hi:[1,0]
	v_mfma_f32_16x16x32_bf16 v[68:71], v[68:71], v[12:15], 0
	s_nop 0
	v_pk_mul_f32 v[144:145], v[64:65], 1.0 op_sel:[1,0] op_sel_hi:[0,0] neg_lo:[1,0] neg_hi:[1,0]
	s_nop 0
	s_waitcnt lgkmcnt(0)
	v_mfma_f32_16x16x32_bf16 v[92:95], v[76:79], v[0:3], v[92:95]
	v_pk_mul_f32 v[142:143], v[66:67], 1.0 op_sel_hi:[1,0] neg_lo:[1,0] neg_hi:[1,0]
	v_mfma_f32_16x16x32_bf16 v[68:71], v[76:79], v[8:11], v[68:71]
	ds_read_b128 v[76:79], v118 offset:4608
	ds_read_b128 v[96:99], v118 offset:4672
	s_nop 3
	s_nop 0
	v_pk_mul_f32 v[156:157], v[92:93], 1.0 op_sel:[1,0] op_sel_hi:[0,0] neg_lo:[1,0] neg_hi:[1,0]
	s_waitcnt lgkmcnt(1)
	v_mfma_f32_16x16x32_bf16 v[128:131], v[76:79], v[4:7], 0
	s_nop 0
	v_pk_mul_f32 v[154:155], v[94:95], 1.0 op_sel_hi:[1,0] neg_lo:[1,0] neg_hi:[1,0]
	v_mfma_f32_16x16x32_bf16 v[76:79], v[76:79], v[12:15], 0
	s_waitcnt lgkmcnt(0)
	v_mfma_f32_16x16x32_bf16 v[130:133], v[96:99], v[0:3], v[128:131]
	v_mfma_f32_16x16x32_bf16 v[76:79], v[96:99], v[8:11], v[76:79]
	ds_read_b128 v[96:99], v118 offset:6912
	ds_read_b128 v[134:137], v118 offset:6976
	s_nop 0
	s_nop 0
	s_waitcnt lgkmcnt(1)
	v_mfma_f32_16x16x32_bf16 v[138:141], v[96:99], v[4:7], 0
	s_nop 0
	v_max_f32_e64 v151, -v130, -v130
	v_max_f32_e64 v153, -v131, -v131
	v_mfma_f32_16x16x32_bf16 v[96:99], v[96:99], v[12:15], 0
	s_nop 0
	s_nop 0
	v_max_f32_e64 v152, -v132, -v132
	s_waitcnt lgkmcnt(0)
	v_mfma_f32_16x16x32_bf16 v[138:141], v[134:137], v[0:3], v[138:141]
	v_max_f32_e64 v150, -v133, -v133
	v_mfma_f32_16x16x32_bf16 v[96:99], v[134:137], v[8:11], v[96:99]
	s_nop 0
	s_nop 4
	v_max_f32_e64 v147, -v138, -v138
	v_max_f32_e64 v149, -v139, -v139
	v_max_f32_e64 v148, -v140, -v140
	v_max_f32_e64 v146, -v141, -v141
	s_nop 0
	v_pk_mul_f32 v[140:141], v[68:69], 1.0 op_sel:[1,0] op_sel_hi:[0,0] neg_lo:[1,0] neg_hi:[1,0]
	s_nop 0
	v_pk_mul_f32 v[138:139], v[70:71], 1.0 op_sel:[1,0] op_sel_hi:[0,0] neg_lo:[1,0] neg_hi:[1,0]
	v_pk_mul_f32 v[136:137], v[76:77], 1.0 op_sel:[1,0] op_sel_hi:[0,0] neg_lo:[1,0] neg_hi:[1,0]
	s_nop 0
	v_pk_mul_f32 v[134:135], v[78:79], 1.0 op_sel:[1,0] op_sel_hi:[0,0] neg_lo:[1,0] neg_hi:[1,0]
	s_nop 0
	v_pk_mul_f32 v[132:133], v[96:97], 1.0 op_sel_hi:[1,0] neg_lo:[1,0] neg_hi:[1,0]
	s_nop 0
	v_pk_mul_f32 v[130:131], v[98:99], 1.0 op_sel:[1,0] op_sel_hi:[0,0] neg_lo:[1,0] neg_hi:[1,0]
	s_cbranch_scc1 .LBB0_764
	v_min_f32_e32 v64, 0x42a00000, v160
	v_mul_f32_e32 v64, 0x3fb8aa3b, v64
	v_exp_f32_e32 v69, v64
	v_min_f32_e32 v64, 0x42a00000, v161
	v_mul_f32_e32 v64, 0x3fb8aa3b, v64
	v_exp_f32_e32 v67, v64
	v_min_f32_e32 v64, 0x42a00000, v159
	v_add_f32_e32 v65, 1.0, v69
	v_mul_f32_e32 v64, 0x3fb8aa3b, v64
	v_rcp_f32_e32 v73, v65
	v_exp_f32_e32 v65, v64
	v_min_f32_e32 v66, 0x42a00000, v157
	v_mul_f32_e32 v66, 0x3fb8aa3b, v66
	v_add_f32_e32 v64, 1.0, v67
	v_exp_f32_e32 v66, v66
	v_rcp_f32_e32 v75, v64
	v_add_f32_e32 v64, 1.0, v65
	v_rcp_f32_e32 v77, v64
	v_min_f32_e32 v64, 0x42a00000, v158
	v_mul_f32_e32 v64, 0x3fb8aa3b, v64
	v_min_f32_e32 v68, 0x42a00000, v156
	v_exp_f32_e32 v71, v64
	v_add_f32_e32 v64, 1.0, v66
	v_mul_f32_e32 v68, 0x3fb8aa3b, v68
	v_rcp_f32_e32 v64, v64
	v_exp_f32_e32 v68, v68
	v_add_u32_e32 v178, s49, v114
	v_add_u32_e32 v180, 16, v178
	v_cmp_lt_i32_e32 vcc, v180, v85
	v_min_f32_e32 v72, 0x42a00000, v154
	v_mul_f32_e32 v72, 0x3fb8aa3b, v72
	v_cndmask_b32_e32 v70, 0, v64, vcc
	v_mul_f32_e32 v64, v66, v64
	v_add_f32_e32 v66, 1.0, v68
	v_rcp_f32_e32 v66, v66
	v_exp_f32_e32 v72, v72
	v_add_u32_e32 v181, 17, v178
	v_cndmask_b32_e32 v64, 1.0, v64, vcc
	v_cmp_lt_i32_e32 vcc, v181, v85
	v_min_f32_e32 v76, 0x42a00000, v155
	v_mul_f32_e32 v76, 0x3fb8aa3b, v76
	v_cndmask_b32_e32 v74, 0, v66, vcc
	v_mul_f32_e32 v66, v68, v66
	v_add_f32_e32 v68, 1.0, v72
	v_rcp_f32_e32 v68, v68
	v_exp_f32_e32 v76, v76
	v_add_u32_e32 v182, 18, v178
	v_cndmask_b32_e32 v66, 1.0, v66, vcc
	v_cmp_lt_i32_e32 vcc, v182, v85
	v_add_u32_e32 v183, 19, v178
	v_min_f32_e32 v98, 0x42a00000, v153
	v_cndmask_b32_e32 v92, 0, v68, vcc
	v_mul_f32_e32 v68, v72, v68
	v_add_f32_e32 v72, 1.0, v76
	v_rcp_f32_e32 v72, v72
	v_cndmask_b32_e32 v68, 1.0, v68, vcc
	v_cmp_lt_i32_e32 vcc, v183, v85
	v_mul_f32_e32 v98, 0x3fb8aa3b, v98
	v_exp_f32_e32 v98, v98
	v_cndmask_b32_e32 v78, 0, v72, vcc
	v_mul_f32_e32 v72, v76, v72
	v_cndmask_b32_e32 v94, 1.0, v72, vcc
	v_mul_f32_e32 v68, v94, v68
	v_mul_f32_e32 v66, v66, v68
	v_mul_f32_e32 v64, v64, v66
	ds_bpermute_b32 v72, v241, v64
	ds_bpermute_b32 v76, v242, v64
	ds_bpermute_b32 v95, v243, v64
	v_add_u32_e32 v184, 32, v178
	v_cmp_lt_i32_e32 vcc, v184, v85
	s_waitcnt lgkmcnt(2)
	v_cndmask_b32_e64 v93, 1.0, v72, s[14:15]
	s_waitcnt lgkmcnt(1)
; __device__ __forceinline__ float fexp(float x) { return __builtin_amdgcn_exp2f(x * 1.44269504f); }
; __device__ __forceinline__ unsigned pack2(float a, float b) { unsigned r; asm volatile("v_cvt_pk_bf16_f32 %0, %1, %2" : "=v"(r) : "v"(a), "v"(b)); return r; }
; __device__ __forceinline__ void item_attn(const Params& p, int l, int aidx) {
;     ...
;             float f[4];
; #pragma unroll
;             for (int j = 0; j < 4; ++j) {
;               const float e = fexp(fminf(-z[m][n][j], 80.f));
;               const float sg = __builtin_amdgcn_rcpf(1.f + e);
;               if (decltype(MASKED)::value) {
;                 const bool ok = (kt * 64 + m * 16 + fq * 4 + j) < qpos;
;                 wgt[m][j] = ok ? sg : 0.f;
;                 f[j] = ok ? e * sg : 1.f;
;               } else { wgt[m][j] = sg; f[j] = e * sg; }
;             }
;             excl[m][3] = 1.f; excl[m][2] = f[3]; excl[m][1] = f[3] * f[2]; excl[m][0] = excl[m][1] * f[1];
;             const float G = excl[m][0] * f[0];
;             const float g1 = __shfl_xor(G, 16), g2 = __shfl_xor(G, 32), g3 = __shfl_xor(G, 48);
;             later[m] = ((fq ^ 1) > fq ? g1 : 1.f) * ((fq ^ 2) > fq ? g2 : 1.f) * ((fq ^ 3) > fq ? g3 : 1.f);
;             TT[m] = (G * g1) * (g2 * g3);
;           }
;           float lm[4]; lm[3] = carry[n]; lm[2] = lm[3] * TT[3]; lm[1] = lm[2] * TT[2]; lm[0] = lm[1] * TT[1];
; #pragma unroll
;           for (int m = 0; m < 4; ++m) {
;             const float base = later[m] * lm[m];
;             float pv[4];
; #pragma unroll
;             for (int j = 0; j < 4; ++j) pv[j] = wgt[m][j] * excl[m][j] * base;
;             pk[m][n][0] = pack2(pv[0], pv[1]); pk[m][n][1] = pack2(pv[2], pv[3]);
;           }
;           carry[n] = lm[0] * TT[0];
	v_cndmask_b32_e64 v96, 1.0, v76, s[16:17]
	v_mul_f32_e32 v93, v93, v96
	v_min_f32_e32 v96, 0x42a00000, v151
	v_mul_f32_e32 v96, 0x3fb8aa3b, v96
	v_exp_f32_e32 v96, v96
	s_waitcnt lgkmcnt(0)
	v_cndmask_b32_e64 v97, 1.0, v95, s[18:19]
	v_mul_f32_e32 v93, v97, v93
	v_min_f32_e32 v99, 0x42a00000, v152
	v_add_f32_e32 v97, 1.0, v96
	v_rcp_f32_e32 v97, v97
	v_mul_f32_e32 v99, 0x3fb8aa3b, v99
	v_exp_f32_e32 v99, v99
	v_add_u32_e32 v185, 33, v178
	v_cndmask_b32_e32 v101, 0, v97, vcc
	v_mul_f32_e32 v96, v96, v97
	v_add_f32_e32 v97, 1.0, v98
	v_rcp_f32_e32 v97, v97
	v_cndmask_b32_e32 v96, 1.0, v96, vcc
	v_cmp_lt_i32_e32 vcc, v185, v85
	v_add_u32_e32 v186, 34, v178
	v_mul_f32_e32 v164, v76, v95
	v_cndmask_b32_e32 v169, 0, v97, vcc
	v_mul_f32_e32 v97, v98, v97
	v_add_f32_e32 v98, 1.0, v99
	v_rcp_f32_e32 v100, v98
	v_min_f32_e32 v98, 0x42a00000, v150
	v_mul_f32_e32 v98, 0x3fb8aa3b, v98
	v_exp_f32_e32 v162, v98
	v_cndmask_b32_e32 v97, 1.0, v97, vcc
	v_cmp_lt_i32_e32 vcc, v186, v85
	v_mul_f32_e32 v99, v99, v100
	v_min_f32_e32 v76, 0x42a00000, v147
	v_cndmask_b32_e32 v98, 0, v100, vcc
	v_add_f32_e32 v100, 1.0, v162
	v_rcp_f32_e32 v100, v100
	v_add_u32_e32 v187, 35, v178
	v_mul_f32_e32 v76, 0x3fb8aa3b, v76
	v_cndmask_b32_e32 v99, 1.0, v99, vcc
	v_cmp_lt_i32_e32 vcc, v187, v85
	v_exp_f32_e32 v76, v76
	v_add_u32_e32 v202, 48, v178
	v_cndmask_b32_e32 v199, 0, v100, vcc
	v_mul_f32_e32 v100, v162, v100
	v_cndmask_b32_e32 v100, 1.0, v100, vcc
	v_mul_f32_e32 v200, v100, v99
	v_min_f32_e32 v99, 0x42a00000, v149
	v_add_f32_e32 v95, 1.0, v76
	v_mul_f32_e32 v99, 0x3fb8aa3b, v99
	v_rcp_f32_e32 v95, v95
	v_exp_f32_e32 v99, v99
	v_cmp_lt_i32_e32 vcc, v202, v85
	v_min_f32_e32 v165, 0x42a00000, v148
	v_mul_f32_e32 v76, v76, v95
	v_cndmask_b32_e32 v203, 0, v95, vcc
	v_add_f32_e32 v95, 1.0, v99
	v_mul_f32_e32 v165, 0x3fb8aa3b, v165
	v_rcp_f32_e32 v95, v95
	v_exp_f32_e32 v165, v165
	v_add_u32_e32 v204, 49, v178
	v_cndmask_b32_e32 v76, 1.0, v76, vcc
	v_cmp_lt_i32_e32 vcc, v204, v85
	v_min_f32_e32 v167, 0x42a00000, v146
	v_mul_f32_e32 v167, 0x3fb8aa3b, v167
	v_cndmask_b32_e32 v205, 0, v95, vcc
	v_mul_f32_e32 v95, v99, v95
	v_add_f32_e32 v99, 1.0, v165
	v_rcp_f32_e32 v99, v99
	v_exp_f32_e32 v167, v167
	v_add_u32_e32 v206, 50, v178
	v_cndmask_b32_e32 v95, 1.0, v95, vcc
	v_cmp_lt_i32_e32 vcc, v206, v85
	v_add_u32_e32 v207, 51, v178
	v_mul_f32_e32 v201, v97, v200
	v_cndmask_b32_e32 v168, 0, v99, vcc
	v_mul_f32_e32 v99, v165, v99
	v_add_f32_e32 v165, 1.0, v167
	v_rcp_f32_e32 v165, v165
	v_cndmask_b32_e32 v99, 1.0, v99, vcc
	v_cmp_lt_i32_e32 vcc, v207, v85
	v_mul_f32_e32 v97, v96, v201
	ds_bpermute_b32 v163, v241, v97
	v_cndmask_b32_e32 v218, 0, v165, vcc
	v_mul_f32_e32 v165, v167, v165
	v_cndmask_b32_e32 v170, 1.0, v165, vcc
	v_mul_f32_e32 v219, v170, v99
	ds_bpermute_b32 v96, v242, v97
	v_mul_f32_e32 v220, v95, v219
	ds_bpermute_b32 v166, v243, v97
	v_mul_f32_e32 v172, v76, v220
	ds_bpermute_b32 v173, v242, v172
	ds_bpermute_b32 v174, v241, v172
	ds_bpermute_b32 v175, v243, v172
	v_mul_f32_e32 v162, v64, v72
	s_waitcnt lgkmcnt(5)
	v_cndmask_b32_e64 v64, 1.0, v163, s[14:15]
	s_waitcnt lgkmcnt(4)
	v_cndmask_b32_e64 v72, 1.0, v96, s[16:17]
	v_mul_f32_e32 v64, v64, v72
	s_waitcnt lgkmcnt(3)
	v_cndmask_b32_e64 v72, 1.0, v166, s[18:19]
	v_mul_f32_e32 v99, v72, v64
	s_waitcnt lgkmcnt(2)
	v_cndmask_b32_e64 v64, 1.0, v173, s[16:17]
	s_waitcnt lgkmcnt(0)
	v_pk_mul_f32 v[172:173], v[172:173], v[174:175]
	v_mul_f32_e32 v176, v97, v163
	v_mov_b32_e32 v97, v172
	v_mov_b32_e32 v167, v173
	v_pk_mul_f32 v[96:97], v[96:97], v[166:167]
	v_mov_b32_e32 v177, v91
	v_pk_mul_f32 v[166:167], v[176:177], v[96:97]
	v_cndmask_b32_e64 v72, 1.0, v174, s[14:15]
	v_mov_b32_e32 v163, v166
	v_mov_b32_e32 v165, v167
	v_pk_mul_f32 v[96:97], v[162:163], v[164:165]
	v_mul_f32_e32 v64, v72, v64
	v_cndmask_b32_e64 v72, 1.0, v175, s[18:19]
	v_mov_b32_e32 v95, v97
	v_mul_f32_e32 v171, v72, v64
	v_mul_f32_e32 v64, v70, v66
	v_pk_mul_f32 v[92:93], v[92:93], v[94:95]
	v_mul_f32_e32 v66, v74, v68
	v_mul_f32_e32 v95, v64, v93
	v_mul_f32_e32 v64, v101, v201
	v_mov_b32_e32 v101, v167
	v_mul_f32_e32 v163, v66, v93
	v_mul_f32_e32 v165, v92, v93
	v_mul_f32_e32 v176, v78, v93
	v_mul_f32_e32 v66, v169, v200
	v_pk_mul_f32 v[92:93], v[98:99], v[100:101]
	v_mov_b32_e32 v169, v91
	v_min_f32_e32 v78, 0x42a00000, v141
	v_mul_f32_e32 v99, v64, v93
	v_mul_f32_e32 v101, v66, v93
	v_mul_f32_e32 v200, v92, v93
	v_mul_f32_e32 v199, v199, v93
	v_pk_mul_f32 v[92:93], v[168:169], v[170:171]
	v_mul_f32_e32 v78, 0x3fb8aa3b, v78
	v_mul_f32_e32 v66, v205, v219
	v_mul_f32_e32 v205, v92, v93
	v_exp_f32_e32 v92, v78
	v_min_f32_e32 v98, 0x42a00000, v140
	v_mul_f32_e32 v98, 0x3fb8aa3b, v98
	v_exp_f32_e32 v98, v98
	v_add_f32_e32 v94, 1.0, v92
	v_rcp_f32_e32 v94, v94
	v_mul_f32_e32 v64, v203, v220
	v_cmp_lt_i32_e32 vcc, v180, v88
	v_mul_f32_e32 v201, v64, v93
	v_mul_f32_e32 v203, v66, v93
	v_mul_f32_e32 v93, v218, v93
	v_cndmask_b32_e32 v218, 0, v94, vcc
	v_mul_f32_e32 v92, v92, v94
	v_min_f32_e32 v94, 0x42a00000, v139
	v_cndmask_b32_e32 v100, 1.0, v92, vcc
	v_add_f32_e32 v92, 1.0, v98
	v_mul_f32_e32 v94, 0x3fb8aa3b, v94
	v_min_f32_e32 v162, 0x42a00000, v138
	v_rcp_f32_e32 v92, v92
	v_exp_f32_e32 v94, v94
	v_mul_f32_e32 v162, 0x3fb8aa3b, v162
	v_exp_f32_e32 v162, v162
	v_cmp_lt_i32_e32 vcc, v181, v88
	v_min_f32_e32 v64, 0x42a00000, v145
	v_mul_f32_e32 v64, 0x3fb8aa3b, v64
	v_cndmask_b32_e32 v219, 0, v92, vcc
	v_mul_f32_e32 v92, v98, v92
	v_add_f32_e32 v98, 1.0, v94
	v_rcp_f32_e32 v98, v98
	v_add_f32_e32 v166, 1.0, v162
	v_rcp_f32_e32 v166, v166
	v_cndmask_b32_e32 v164, 1.0, v92, vcc
	v_cmp_lt_i32_e32 vcc, v182, v88
	v_mul_f32_e32 v94, v94, v98
; __device__ __forceinline__ float fexp(float x) { return __builtin_amdgcn_exp2f(x * 1.44269504f); }
; __device__ __forceinline__ unsigned pack2(float a, float b) { unsigned r; asm volatile("v_cvt_pk_bf16_f32 %0, %1, %2" : "=v"(r) : "v"(a), "v"(b)); return r; }
; __device__ __forceinline__ void item_attn(const Params& p, int l, int aidx) {
;     ...
;             float f[4];
; #pragma unroll
;             for (int j = 0; j < 4; ++j) {
;               const float e = fexp(fminf(-z[m][n][j], 80.f));
;               const float sg = __builtin_amdgcn_rcpf(1.f + e);
;               if (decltype(MASKED)::value) {
;                 const bool ok = (kt * 64 + m * 16 + fq * 4 + j) < qpos;
;                 wgt[m][j] = ok ? sg : 0.f;
;                 f[j] = ok ? e * sg : 1.f;
;               } else { wgt[m][j] = sg; f[j] = e * sg; }
;             }
;             excl[m][3] = 1.f; excl[m][2] = f[3]; excl[m][1] = f[3] * f[2]; excl[m][0] = excl[m][1] * f[1];
;             const float G = excl[m][0] * f[0];
;             const float g1 = __shfl_xor(G, 16), g2 = __shfl_xor(G, 32), g3 = __shfl_xor(G, 48);
;             later[m] = ((fq ^ 1) > fq ? g1 : 1.f) * ((fq ^ 2) > fq ? g2 : 1.f) * ((fq ^ 3) > fq ? g3 : 1.f);
;             TT[m] = (G * g1) * (g2 * g3);
;           }
;           float lm[4]; lm[3] = carry[n]; lm[2] = lm[3] * TT[3]; lm[1] = lm[2] * TT[2]; lm[0] = lm[1] * TT[1];
; #pragma unroll
;           for (int m = 0; m < 4; ++m) {
;             const float base = later[m] * lm[m];
;             float pv[4];
; #pragma unroll
;             for (int j = 0; j < 4; ++j) pv[j] = wgt[m][j] * excl[m][j] * base;
;             pk[m][n][0] = pack2(pv[0], pv[1]); pk[m][n][1] = pack2(pv[2], pv[3]);
;           }
;           carry[n] = lm[0] * TT[0];
	v_min_f32_e32 v66, 0x42a00000, v144
	v_cndmask_b32_e32 v92, 0, v98, vcc
	v_cndmask_b32_e32 v98, 1.0, v94, vcc
	v_mul_f32_e32 v94, v162, v166
	v_min_f32_e32 v162, 0x42a00000, v137
	v_mul_f32_e32 v162, 0x3fb8aa3b, v162
	v_cmp_lt_i32_e32 vcc, v183, v88
	v_exp_f32_e32 v162, v162
	v_exp_f32_e32 v68, v64
	v_cndmask_b32_e32 v94, 1.0, v94, vcc
	v_mul_f32_e32 v221, v94, v98
	v_mul_f32_e32 v222, v164, v221
	v_mul_f32_e32 v183, v100, v222
	v_add_f32_e32 v98, 1.0, v162
	v_min_f32_e32 v100, 0x42a00000, v136
	v_rcp_f32_e32 v98, v98
	v_mul_f32_e32 v100, 0x3fb8aa3b, v100
	v_exp_f32_e32 v100, v100
	v_cndmask_b32_e32 v220, 0, v166, vcc
	v_cmp_lt_i32_e32 vcc, v184, v88
	v_min_f32_e32 v164, 0x42a00000, v135
	v_mul_f32_e32 v164, 0x3fb8aa3b, v164
	v_cndmask_b32_e32 v184, 0, v98, vcc
	v_mul_f32_e32 v98, v162, v98
	v_cndmask_b32_e32 v162, 1.0, v98, vcc
	v_add_f32_e32 v98, 1.0, v100
	v_min_f32_e32 v166, 0x42a00000, v134
	v_rcp_f32_e32 v98, v98
	v_exp_f32_e32 v164, v164
	v_mul_f32_e32 v166, 0x3fb8aa3b, v166
	v_exp_f32_e32 v166, v166
	v_cmp_lt_i32_e32 vcc, v185, v88
	v_mul_f32_e32 v66, 0x3fb8aa3b, v66
	v_exp_f32_e32 v66, v66
	v_cndmask_b32_e32 v185, 0, v98, vcc
	v_mul_f32_e32 v98, v100, v98
	v_add_f32_e32 v100, 1.0, v164
	v_rcp_f32_e32 v100, v100
	v_add_f32_e32 v168, 1.0, v166
	v_rcp_f32_e32 v168, v168
	v_cndmask_b32_e32 v167, 1.0, v98, vcc
	v_cmp_lt_i32_e32 vcc, v186, v88
	v_add_f32_e32 v64, 1.0, v68
	v_min_f32_e32 v70, 0x42a00000, v142
	v_cndmask_b32_e32 v98, 0, v100, vcc
	v_mul_f32_e32 v100, v164, v100
	v_cndmask_b32_e32 v164, 1.0, v100, vcc
	v_mul_f32_e32 v100, v166, v168
	v_min_f32_e32 v166, 0x42a00000, v132
	v_mul_f32_e32 v166, 0x3fb8aa3b, v166
	v_cmp_lt_i32_e32 vcc, v187, v88
	v_exp_f32_e32 v166, v166
	v_rcp_f32_e32 v72, v64
	v_cndmask_b32_e32 v100, 1.0, v100, vcc
	v_mul_f32_e32 v187, v100, v164
	v_mul_f32_e32 v223, v167, v187
	v_mul_f32_e32 v224, v162, v223
	v_add_f32_e32 v162, 1.0, v166
	v_min_f32_e32 v164, 0x42a00000, v133
	v_rcp_f32_e32 v162, v162
	v_mul_f32_e32 v164, 0x3fb8aa3b, v164
	v_exp_f32_e32 v164, v164
	v_cndmask_b32_e32 v186, 0, v168, vcc
	v_cmp_lt_i32_e32 vcc, v202, v88
	v_add_f32_e32 v64, 1.0, v66
	v_min_f32_e32 v168, 0x42a00000, v130
	v_cndmask_b32_e32 v202, 0, v162, vcc
	v_mul_f32_e32 v162, v166, v162
	v_min_f32_e32 v166, 0x42a00000, v131
	v_cndmask_b32_e32 v167, 1.0, v162, vcc
	v_add_f32_e32 v162, 1.0, v164
	v_mul_f32_e32 v166, 0x3fb8aa3b, v166
	v_rcp_f32_e32 v162, v162
	v_exp_f32_e32 v166, v166
	v_mul_f32_e32 v70, 0x3fb8aa3b, v70
	v_rcp_f32_e32 v74, v64
	v_min_f32_e32 v64, 0x42a00000, v143
	v_mul_f32_e32 v168, 0x3fb8aa3b, v168
	v_exp_f32_e32 v70, v70
	v_mul_f32_e32 v64, 0x3fb8aa3b, v64
	v_exp_f32_e32 v168, v168
	v_exp_f32_e32 v64, v64
	v_cmp_lt_i32_e32 vcc, v204, v88
	v_add_f32_e32 v76, 1.0, v70
	v_add_f32_e32 v169, 1.0, v168
	v_cndmask_b32_e32 v204, 0, v162, vcc
	v_mul_f32_e32 v162, v164, v162
	v_add_f32_e32 v164, 1.0, v166
	v_rcp_f32_e32 v164, v164
	v_add_f32_e32 v79, 1.0, v71
	v_rcp_f32_e32 v78, v76
	v_add_f32_e32 v76, 1.0, v64
	v_rcp_f32_e32 v169, v169
	v_rcp_f32_e32 v79, v79
	v_rcp_f32_e32 v76, v76
	v_cndmask_b32_e32 v180, 1.0, v162, vcc
	v_cmp_lt_i32_e32 vcc, v206, v88
	v_add_u32_e32 v179, 1, v178
	v_pk_mul_f32 v[70:71], v[70:71], v[78:79]
	v_cndmask_b32_e32 v162, 0, v164, vcc
	v_mul_f32_e32 v164, v166, v164
	v_cndmask_b32_e32 v166, 1.0, v164, vcc
	v_cmp_lt_i32_e32 vcc, v207, v88
	v_mul_f32_e32 v164, v168, v169
	v_or_b32_e32 v168, 3, v178
	v_cndmask_b32_e32 v206, 0, v169, vcc
	v_or_b32_e32 v169, 2, v178
	v_cndmask_b32_e32 v164, 1.0, v164, vcc
	v_cmp_lt_i32_e64 s[24:25], v169, v85
	v_cmp_lt_i32_e64 s[26:27], v168, v85
	v_pk_mul_f32 v[64:65], v[64:65], v[76:77]
	v_mul_f32_e32 v207, v164, v166
	v_cmp_lt_i32_e64 s[22:23], v179, v85
	v_cndmask_b32_e64 v166, 0, v77, s[24:25]
	v_cndmask_b32_e64 v227, 0, v79, s[26:27]
	v_pk_mul_f32 v[66:67], v[66:67], v[74:75]
	v_cndmask_b32_e64 v71, 1.0, v71, s[26:27]
	v_cmp_lt_i32_e64 s[26:27], v169, v88
	v_cndmask_b32_e64 v169, 1.0, v65, s[24:25]
	v_cmp_lt_i32_e64 s[24:25], v168, v88
	v_cmp_lt_i32_e32 vcc, v178, v85
	v_cndmask_b32_e64 v226, 0, v75, s[22:23]
	v_pk_mul_f32 v[68:69], v[68:69], v[72:73]
	v_cndmask_b32_e64 v67, 1.0, v67, s[22:23]
	v_cmp_lt_i32_e64 s[22:23], v179, v88
	v_cndmask_b32_e64 v70, 1.0, v70, s[26:27]
	v_cndmask_b32_e64 v168, 1.0, v64, s[24:25]
	v_cndmask_b32_e32 v225, 0, v73, vcc
	v_cndmask_b32_e32 v69, 1.0, v69, vcc
	v_cmp_lt_i32_e32 vcc, v178, v88
	v_cndmask_b32_e64 v66, 1.0, v66, s[22:23]
	v_pk_mul_f32 v[170:171], v[70:71], v[168:169]
	v_cndmask_b32_e32 v68, 1.0, v68, vcc
	v_pk_mul_f32 v[172:173], v[66:67], v[170:171]
	v_mul_f32_e32 v228, v180, v207
	v_pk_mul_f32 v[174:175], v[68:69], v[172:173]
	ds_bpermute_b32 v177, v241, v175
	ds_bpermute_b32 v179, v242, v175
	ds_bpermute_b32 v181, v243, v175
	v_pk_mul_f32 v[96:97], v[96:97], v[96:97] op_sel:[0,1] op_sel_hi:[1,0]
	v_mul_f32_e32 v182, v167, v228
	s_waitcnt lgkmcnt(2)
; __device__ __forceinline__ float fexp(float x) { return __builtin_amdgcn_exp2f(x * 1.44269504f); }
; __device__ __forceinline__ unsigned pack2(float a, float b) { unsigned r; asm volatile("v_cvt_pk_bf16_f32 %0, %1, %2" : "=v"(r) : "v"(a), "v"(b)); return r; }
; __device__ __forceinline__ void item_attn(const Params& p, int l, int aidx) {
;     ...
;             float f[4];
; #pragma unroll
;             for (int j = 0; j < 4; ++j) {
;               const float e = fexp(fminf(-z[m][n][j], 80.f));
;               const float sg = __builtin_amdgcn_rcpf(1.f + e);
;               if (decltype(MASKED)::value) {
;                 const bool ok = (kt * 64 + m * 16 + fq * 4 + j) < qpos;
;                 wgt[m][j] = ok ? sg : 0.f;
;                 f[j] = ok ? e * sg : 1.f;
;               } else { wgt[m][j] = sg; f[j] = e * sg; }
;             }
;             excl[m][3] = 1.f; excl[m][2] = f[3]; excl[m][1] = f[3] * f[2]; excl[m][0] = excl[m][1] * f[1];
;             const float G = excl[m][0] * f[0];
;             const float g1 = __shfl_xor(G, 16), g2 = __shfl_xor(G, 32), g3 = __shfl_xor(G, 48);
;             later[m] = ((fq ^ 1) > fq ? g1 : 1.f) * ((fq ^ 2) > fq ? g2 : 1.f) * ((fq ^ 3) > fq ? g3 : 1.f);
;             TT[m] = (G * g1) * (g2 * g3);
;           }
;           float lm[4]; lm[3] = carry[n]; lm[2] = lm[3] * TT[3]; lm[1] = lm[2] * TT[2]; lm[0] = lm[1] * TT[1];
; #pragma unroll
;           for (int m = 0; m < 4; ++m) {
;             const float base = later[m] * lm[m];
;             float pv[4];
; #pragma unroll
;             for (int j = 0; j < 4; ++j) pv[j] = wgt[m][j] * excl[m][j] * base;
;             pk[m][n][0] = pack2(pv[0], pv[1]); pk[m][n][1] = pack2(pv[2], pv[3]);
;           }
;           carry[n] = lm[0] * TT[0];
	v_cndmask_b32_e64 v64, 1.0, v177, s[14:15]
	s_waitcnt lgkmcnt(1)
	v_cndmask_b32_e64 v65, 1.0, v179, s[16:17]
	v_mul_f32_e32 v64, v64, v65
	s_waitcnt lgkmcnt(0)
	v_cndmask_b32_e64 v65, 1.0, v181, s[18:19]
	v_mul_f32_e32 v167, v65, v64
	v_pk_mov_b32 v[64:65], v[70:71], v[96:97] op_sel:[1,0]
	v_mul_f32_e32 v66, v225, v173
	v_mul_f32_e32 v67, v226, v171
	v_pk_mul_f32 v[64:65], v[166:167], v[64:65]
	ds_bpermute_b32 v178, v242, v174
	v_mul_f32_e32 v66, v66, v65
	v_mul_f32_e32 v67, v67, v65
	v_mul_f32_e32 v64, v64, v65
	v_mul_f32_e32 v65, v227, v65
	v_cvt_pk_bf16_f32 v68, v66, v67
	v_cvt_pk_bf16_f32 v69, v64, v65
	v_cvt_pk_bf16_f32 v70, v95, v163
	v_cvt_pk_bf16_f32 v71, v165, v176
	ds_bpermute_b32 v176, v241, v174
	ds_bpermute_b32 v180, v243, v174
	ds_bpermute_b32 v75, v241, v183
	ds_bpermute_b32 v77, v242, v183
	ds_bpermute_b32 v79, v243, v183
	v_cndmask_b32_e64 v97, 0, v74, s[22:23]
	s_waitcnt lgkmcnt(4)
	v_cndmask_b32_e64 v73, 1.0, v176, s[14:15]
	v_cndmask_b32_e64 v74, 1.0, v178, s[16:17]
	v_mul_f32_e32 v73, v73, v74
	s_waitcnt lgkmcnt(3)
	v_cndmask_b32_e64 v74, 1.0, v180, s[18:19]
	v_cvt_pk_bf16_f32 v64, v99, v101
	v_cndmask_b32_e64 v101, 0, v76, s[24:25]
	v_mul_f32_e32 v73, v74, v73
	s_waitcnt lgkmcnt(2)
	v_cndmask_b32_e64 v74, 1.0, v75, s[14:15]
	s_waitcnt lgkmcnt(1)
	v_cndmask_b32_e64 v76, 1.0, v77, s[16:17]
	v_mul_f32_e32 v74, v74, v76
	s_waitcnt lgkmcnt(0)
	v_cndmask_b32_e64 v76, 1.0, v79, s[18:19]
	v_cvt_pk_bf16_f32 v65, v200, v199
	v_cvt_pk_bf16_f32 v66, v201, v203
	v_cvt_pk_bf16_f32 v67, v205, v93
	v_mul_f32_e32 v93, v76, v74
	ds_bpermute_b32 v163, v241, v224
	ds_bpermute_b32 v74, v242, v224
	v_cndmask_b32_e32 v95, 0, v72, vcc
	v_cndmask_b32_e64 v72, 0, v78, s[26:27]
	ds_bpermute_b32 v78, v243, v224
	v_pk_mul_f32 v[166:167], v[174:175], v[176:177]
	v_mul_f32_e32 v76, v183, v75
	ds_bpermute_b32 v183, v242, v182
	ds_bpermute_b32 v176, v241, v182
	ds_bpermute_b32 v177, v243, v182
	v_pk_mul_f32 v[174:175], v[178:179], v[180:181]
	s_waitcnt lgkmcnt(5)
	v_cndmask_b32_e64 v75, 1.0, v163, s[14:15]
	v_pk_mul_f32 v[166:167], v[166:167], v[174:175]
	v_mul_f32_e32 v174, v77, v79
	s_waitcnt lgkmcnt(4)
	v_cndmask_b32_e64 v77, 1.0, v74, s[16:17]
	v_mul_f32_e32 v75, v75, v77
	s_waitcnt lgkmcnt(3)
	v_cndmask_b32_e64 v77, 1.0, v78, s[18:19]
	v_mul_f32_e32 v99, v77, v75
	s_waitcnt lgkmcnt(2)
	v_cndmask_b32_e64 v75, 1.0, v183, s[16:17]
	s_waitcnt lgkmcnt(1)
	v_cndmask_b32_e64 v77, 1.0, v176, s[14:15]
	v_mul_f32_e32 v75, v77, v75
	s_waitcnt lgkmcnt(0)
	v_cndmask_b32_e64 v77, 1.0, v177, s[18:19]
	v_pk_mul_f32 v[176:177], v[182:183], v[176:177]
	v_mul_f32_e32 v165, v77, v75
	v_mov_b32_e32 v75, v176
	v_mov_b32_e32 v79, v177
	v_mul_f32_e32 v178, v224, v163
	v_pk_mul_f32 v[74:75], v[74:75], v[78:79]
	v_mov_b32_e32 v179, v90
	v_pk_mul_f32 v[78:79], v[178:179], v[74:75]
	v_mov_b32_e32 v163, v90
	v_mov_b32_e32 v77, v78
	v_mov_b32_e32 v175, v79
	v_pk_mul_f32 v[74:75], v[76:77], v[174:175]
	v_mul_f32_e32 v76, v97, v170
	v_pk_mul_f32 v[174:175], v[74:75], v[74:75] op_sel:[0,1] op_sel_hi:[1,0]
	v_mul_f32_e32 v74, v95, v172
	v_mov_b32_e32 v169, v174
	v_pk_mul_f32 v[72:73], v[72:73], v[168:169]
	v_mov_b32_e32 v95, v75
	v_mul_f32_e32 v74, v74, v73
	v_mul_f32_e32 v76, v76, v73
	v_mul_f32_e32 v77, v72, v73
	v_mul_f32_e32 v73, v101, v73
	v_cvt_pk_bf16_f32 v72, v74, v76
	v_cvt_pk_bf16_f32 v73, v77, v73
	v_mul_f32_e32 v76, v218, v222
	v_mul_f32_e32 v77, v219, v221
	v_pk_mul_f32 v[74:75], v[92:93], v[94:95]
	v_mov_b32_e32 v101, v79
	v_mul_f32_e32 v76, v76, v75
	v_mul_f32_e32 v77, v77, v75
	v_mul_f32_e32 v78, v74, v75
	v_mul_f32_e32 v75, v220, v75
	v_cvt_pk_bf16_f32 v74, v76, v77
	v_cvt_pk_bf16_f32 v75, v78, v75
	v_mul_f32_e32 v78, v184, v223
	v_mul_f32_e32 v92, v185, v187
	v_pk_mul_f32 v[76:77], v[98:99], v[100:101]
	v_mul_f32_e32 v93, v204, v207
	v_mul_f32_e32 v78, v78, v77
	v_mul_f32_e32 v79, v92, v77
	v_mul_f32_e32 v92, v76, v77
	v_mul_f32_e32 v77, v186, v77
	v_cvt_pk_bf16_f32 v76, v78, v79
	v_cvt_pk_bf16_f32 v77, v92, v77
	v_mul_f32_e32 v92, v202, v228
	v_pk_mul_f32 v[78:79], v[162:163], v[164:165]
	v_mov_b32_e32 v175, v96
	v_mul_f32_e32 v92, v92, v79
	v_mul_f32_e32 v93, v93, v79
	v_mul_f32_e32 v94, v78, v79
	v_mul_f32_e32 v79, v206, v79
	v_cvt_pk_bf16_f32 v78, v92, v93
	v_pk_mul_f32 v[92:93], v[166:167], v[174:175]
	s_mov_b64 s[0:1], 0
	v_cvt_pk_bf16_f32 v79, v94, v79
